# GEMM K-loop variant: kk1 A fragments read in second MFMA group
# speedup vs baseline: 1.0013x; 1.0013x over previous
.LBB0_212:
	s_add_i32 s1, s0, 0x10000
	s_and_b32 s11, s1, 0x10000
	s_waitcnt vmcnt(0)
	s_barrier
	s_and_b32 s0, s0, 0x10000
	s_add_i32 s0, s0, 0
	v_add_u32_e32 v155, s0, v153
	v_add_u32_e32 v164, v155, v151
	ds_read_b128 v[156:159], v164
	ds_read_b128 v[160:163], v164 offset:2048
	ds_read_b128 v[178:181], v164 offset:4096
	ds_read_b128 v[182:185], v164 offset:6144
	v_add_u32_e32 v249, v155, v150
	v_add_u32_e32 v164, s0, v154
	v_add_u32_e32 v165, v164, v151
	ds_read_b128 v[186:189], v165 offset:32768
	ds_read_b128 v[192:195], v165 offset:34816
	ds_read_b128 v[198:201], v165 offset:36864
	ds_read_b128 v[204:207], v165 offset:38912
	v_add_u32_e32 v248, v164, v150
	v_add_u32_e32 v251, s11, v152
	v_add_u32_e32 v240, 0x2000, v251
	v_readfirstlane_b32 s11, v251
	v_lshl_add_u64 v[174:175], v[144:145], 0, s[8:9]
	s_mov_b32 m0, s11
	v_readfirstlane_b32 s11, v240
	v_add_u32_e32 v240, 0x4000, v251
	global_load_lds_dwordx4 v[174:175], off
	v_lshl_add_u64 v[174:175], v[134:135], 0, s[8:9]
	s_mov_b32 m0, s11
	s_waitcnt lgkmcnt(0)
	v_mfma_f32_16x16x32_bf16 v[124:127], v[156:159], v[186:189], v[124:127]
	ds_read_b128 v[224:227], v165 offset:40960
	v_mfma_f32_16x16x32_bf16 v[120:123], v[156:159], v[192:195], v[120:123]
	ds_read_b128 v[228:231], v165 offset:43008
	v_readfirstlane_b32 s11, v240
	v_add_u32_e32 v240, 0x6000, v251
	v_mfma_f32_16x16x32_bf16 v[116:119], v[156:159], v[198:201], v[116:119]
	ds_read_b128 v[232:235], v165 offset:45056
	global_load_lds_dwordx4 v[174:175], off
	v_lshl_add_u64 v[174:175], v[132:133], 0, s[8:9]
	v_mfma_f32_16x16x32_bf16 v[112:115], v[156:159], v[204:207], v[112:115]
	ds_read_b128 v[236:239], v165 offset:47104
	s_mov_b32 m0, s11
	v_readfirstlane_b32 s11, v240
	v_mfma_f32_16x16x32_bf16 v[104:107], v[160:163], v[186:189], v[104:107]
	global_load_lds_dwordx4 v[174:175], off
	v_lshl_add_u64 v[174:175], v[130:131], 0, s[8:9]
	v_mfma_f32_16x16x32_bf16 v[96:99], v[160:163], v[192:195], v[96:99]
	s_mov_b32 m0, s11
	v_add_u32_e32 v250, 0x8000, v251
	v_mfma_f32_16x16x32_bf16 v[88:91], v[160:163], v[198:201], v[88:91]
	global_load_lds_dwordx4 v[174:175], off
	v_lshl_add_u64 v[174:175], v[128:129], 0, s[8:9]
	v_mfma_f32_16x16x32_bf16 v[80:83], v[160:163], v[204:207], v[80:83]
	v_readfirstlane_b32 s11, v250
	v_add_u32_e32 v250, 0xa000, v251
	v_mfma_f32_16x16x32_bf16 v[72:75], v[178:181], v[186:189], v[72:75]
	v_lshl_add_u64 v[240:241], v[174:175], 0, s[66:67]
	s_mov_b32 m0, s11
	v_mfma_f32_16x16x32_bf16 v[64:67], v[178:181], v[192:195], v[64:67]
	s_mov_b64 s[12:13], 0x22080
	v_readfirstlane_b32 s11, v250
	v_mfma_f32_16x16x32_bf16 v[56:59], v[178:181], v[198:201], v[56:59]
	v_add_u32_e32 v250, 0xc000, v251
	global_load_lds_dwordx4 v[240:241], off
	v_mfma_f32_16x16x32_bf16 v[48:51], v[178:181], v[204:207], v[48:51]
	v_lshl_add_u64 v[240:241], v[174:175], 0, s[12:13]
	s_mov_b32 m0, s11
	v_mfma_f32_16x16x32_bf16 v[40:43], v[182:185], v[186:189], v[40:43]
	s_mov_b64 s[12:13], 0x44080
	v_readfirstlane_b32 s11, v250
	v_mfma_f32_16x16x32_bf16 v[32:35], v[182:185], v[192:195], v[32:35]
	v_add_u32_e32 v251, 0xe000, v251
	global_load_lds_dwordx4 v[240:241], off
	v_mfma_f32_16x16x32_bf16 v[24:27], v[182:185], v[198:201], v[24:27]
	v_lshl_add_u64 v[240:241], v[174:175], 0, s[12:13]
	s_mov_b32 m0, s11
	v_mfma_f32_16x16x32_bf16 v[16:19], v[182:185], v[204:207], v[16:19]
	s_mov_b64 s[12:13], 0x66080
	v_readfirstlane_b32 s11, v251
	s_waitcnt lgkmcnt(0)
	v_mfma_f32_16x16x32_bf16 v[100:103], v[156:159], v[224:227], v[100:103]
	ds_read_b128 v[208:211], v249
	global_load_lds_dwordx4 v[240:241], off
	v_lshl_add_u64 v[174:175], v[174:175], 0, s[12:13]
	v_mfma_f32_16x16x32_bf16 v[92:95], v[156:159], v[228:231], v[92:95]
	ds_read_b128 v[212:215], v249 offset:2048
	s_mov_b32 m0, s11
	global_load_lds_dwordx4 v[174:175], off
	v_mfma_f32_16x16x32_bf16 v[84:87], v[156:159], v[232:235], v[84:87]
	ds_read_b128 v[216:219], v249 offset:4096
	v_mfma_f32_16x16x32_bf16 v[76:79], v[156:159], v[236:239], v[76:79]
	ds_read_b128 v[220:223], v249 offset:6144
	v_mfma_f32_16x16x32_bf16 v[68:71], v[160:163], v[224:227], v[68:71]
	v_mfma_f32_16x16x32_bf16 v[60:63], v[160:163], v[228:231], v[60:63]
	v_mfma_f32_16x16x32_bf16 v[52:55], v[160:163], v[232:235], v[52:55]
	ds_read_b128 v[186:189], v248 offset:32768
	v_mfma_f32_16x16x32_bf16 v[44:47], v[160:163], v[236:239], v[44:47]
	ds_read_b128 v[192:195], v248 offset:34816
	v_mfma_f32_16x16x32_bf16 v[36:39], v[178:181], v[224:227], v[36:39]
	ds_read_b128 v[198:201], v248 offset:36864
	v_mfma_f32_16x16x32_bf16 v[28:31], v[178:181], v[228:231], v[28:31]
	ds_read_b128 v[204:207], v248 offset:38912
	v_mfma_f32_16x16x32_bf16 v[20:23], v[178:181], v[232:235], v[20:23]
	v_mfma_f32_16x16x32_bf16 v[12:15], v[178:181], v[236:239], v[12:15]
	v_mfma_f32_16x16x32_bf16 v[8:11], v[182:185], v[224:227], v[8:11]
	v_mfma_f32_16x16x32_bf16 v[4:7], v[182:185], v[228:231], v[4:7]
	v_mfma_f32_16x16x32_bf16 v[0:3], v[182:185], v[232:235], v[0:3]
	v_mfma_f32_16x16x32_bf16 v[108:111], v[182:185], v[236:239], v[108:111]
	s_waitcnt lgkmcnt(0)
	v_mfma_f32_16x16x32_bf16 v[124:127], v[208:211], v[186:189], v[124:127]
	ds_read_b128 v[224:227], v248 offset:40960
	v_mfma_f32_16x16x32_bf16 v[120:123], v[208:211], v[192:195], v[120:123]
	ds_read_b128 v[228:231], v248 offset:43008
	v_mfma_f32_16x16x32_bf16 v[116:119], v[208:211], v[198:201], v[116:119]
	ds_read_b128 v[232:235], v248 offset:45056
	v_mfma_f32_16x16x32_bf16 v[112:115], v[208:211], v[204:207], v[112:115]
	ds_read_b128 v[236:239], v248 offset:47104
	v_mfma_f32_16x16x32_bf16 v[104:107], v[212:215], v[186:189], v[104:107]
	v_mfma_f32_16x16x32_bf16 v[96:99], v[212:215], v[192:195], v[96:99]
	v_mfma_f32_16x16x32_bf16 v[88:91], v[212:215], v[198:201], v[88:91]
	v_mfma_f32_16x16x32_bf16 v[80:83], v[212:215], v[204:207], v[80:83]
	v_mfma_f32_16x16x32_bf16 v[72:75], v[216:219], v[186:189], v[72:75]
	v_mfma_f32_16x16x32_bf16 v[64:67], v[216:219], v[192:195], v[64:67]
	v_mfma_f32_16x16x32_bf16 v[56:59], v[216:219], v[198:201], v[56:59]
	v_mfma_f32_16x16x32_bf16 v[48:51], v[216:219], v[204:207], v[48:51]
	v_mfma_f32_16x16x32_bf16 v[40:43], v[220:223], v[186:189], v[40:43]
	v_mfma_f32_16x16x32_bf16 v[32:35], v[220:223], v[192:195], v[32:35]
	v_mfma_f32_16x16x32_bf16 v[24:27], v[220:223], v[198:201], v[24:27]
	v_mfma_f32_16x16x32_bf16 v[16:19], v[220:223], v[204:207], v[16:19]
	s_waitcnt lgkmcnt(0)
	v_mfma_f32_16x16x32_bf16 v[100:103], v[208:211], v[224:227], v[100:103]
	v_mfma_f32_16x16x32_bf16 v[92:95], v[208:211], v[228:231], v[92:95]
	v_mfma_f32_16x16x32_bf16 v[84:87], v[208:211], v[232:235], v[84:87]
	v_mfma_f32_16x16x32_bf16 v[76:79], v[208:211], v[236:239], v[76:79]
	v_mfma_f32_16x16x32_bf16 v[68:71], v[212:215], v[224:227], v[68:71]
	v_mfma_f32_16x16x32_bf16 v[60:63], v[212:215], v[228:231], v[60:63]
	v_mfma_f32_16x16x32_bf16 v[52:55], v[212:215], v[232:235], v[52:55]
	v_mfma_f32_16x16x32_bf16 v[44:47], v[212:215], v[236:239], v[44:47]
	v_mfma_f32_16x16x32_bf16 v[36:39], v[216:219], v[224:227], v[36:39]
	v_mfma_f32_16x16x32_bf16 v[28:31], v[216:219], v[228:231], v[28:31]
	v_mfma_f32_16x16x32_bf16 v[20:23], v[216:219], v[232:235], v[20:23]
	v_mfma_f32_16x16x32_bf16 v[12:15], v[216:219], v[236:239], v[12:15]
	s_add_u32 s8, s8, 0x80
	s_addc_u32 s9, s9, 0
	s_cmpk_eq_i32 s8, 0x780
	s_mov_b32 s0, s1
	v_mfma_f32_16x16x32_bf16 v[8:11], v[220:223], v[224:227], v[8:11]
	v_mfma_f32_16x16x32_bf16 v[4:7], v[220:223], v[228:231], v[4:7]
	v_mfma_f32_16x16x32_bf16 v[0:3], v[220:223], v[232:235], v[0:3]
	v_mfma_f32_16x16x32_bf16 v[108:111], v[220:223], v[236:239], v[108:111]
	s_cbranch_scc0 .LBB0_212
	s_add_i32 s0, 0, 0x10000
	v_add_u32_e32 v144, s0, v154
	v_add_u32_e32 v162, s0, v153
	v_add_u32_e32 v145, v144, v151
	v_add_u32_e32 v151, v162, v151
	s_waitcnt vmcnt(0)
	s_barrier
	ds_read_b128 v[128:131], v145 offset:38912
	ds_read_b128 v[132:135], v145 offset:36864
	ds_read_b128 v[154:157], v145 offset:34816
	ds_read_b128 v[158:161], v145 offset:32768
	ds_read_b128 v[178:181], v151 offset:6144
	ds_read_b128 v[182:185], v151 offset:4096
	ds_read_b128 v[186:189], v151 offset:2048
	ds_read_b128 v[204:207], v151
	s_waitcnt lgkmcnt(0)
	v_mfma_f32_16x16x32_bf16 v[124:127], v[204:207], v[158:161], v[124:127]
	v_mfma_f32_16x16x32_bf16 v[120:123], v[204:207], v[154:157], v[120:123]
	v_mfma_f32_16x16x32_bf16 v[116:119], v[204:207], v[132:135], v[116:119]
	v_mfma_f32_16x16x32_bf16 v[112:115], v[204:207], v[128:131], v[112:115]
	v_mfma_f32_16x16x32_bf16 v[104:107], v[186:189], v[158:161], v[104:107]
	v_mfma_f32_16x16x32_bf16 v[72:75], v[182:185], v[158:161], v[72:75]
	v_mfma_f32_16x16x32_bf16 v[64:67], v[182:185], v[154:157], v[64:67]
	v_mfma_f32_16x16x32_bf16 v[56:59], v[182:185], v[132:135], v[56:59]
	v_mfma_f32_16x16x32_bf16 v[48:51], v[182:185], v[128:131], v[48:51]
	v_mfma_f32_16x16x32_bf16 v[208:211], v[186:189], v[154:157], v[96:99]
	v_mfma_f32_16x16x32_bf16 v[212:215], v[186:189], v[132:135], v[88:91]
	v_mfma_f32_16x16x32_bf16 v[216:219], v[186:189], v[128:131], v[80:83]
	v_mfma_f32_16x16x32_bf16 v[158:161], v[178:181], v[158:161], v[40:43]
	v_mfma_f32_16x16x32_bf16 v[152:155], v[178:181], v[154:157], v[32:35]
	v_mfma_f32_16x16x32_bf16 v[132:135], v[178:181], v[132:135], v[24:27]
	v_mfma_f32_16x16x32_bf16 v[128:131], v[178:181], v[128:131], v[16:19]
	s_nop 2
	ds_read_b128 v[16:19], v145 offset:40960
	ds_read_b128 v[24:27], v145 offset:43008
	ds_read_b128 v[32:35], v145 offset:45056
	ds_read_b128 v[40:43], v145 offset:47104
	s_waitcnt lgkmcnt(0)
	v_mfma_f32_16x16x32_bf16 v[100:103], v[204:207], v[16:19], v[100:103]
	v_mfma_f32_16x16x32_bf16 v[92:95], v[204:207], v[24:27], v[92:95]
	v_mfma_f32_16x16x32_bf16 v[220:223], v[204:207], v[32:35], v[84:87]
	v_mfma_f32_16x16x32_bf16 v[76:79], v[204:207], v[40:43], v[76:79]
	v_mfma_f32_16x16x32_bf16 v[68:71], v[186:189], v[16:19], v[68:71]
	v_mfma_f32_16x16x32_bf16 v[60:63], v[186:189], v[24:27], v[60:63]
	v_mfma_f32_16x16x32_bf16 v[204:207], v[186:189], v[32:35], v[52:55]
	v_mfma_f32_16x16x32_bf16 v[44:47], v[186:189], v[40:43], v[44:47]
	v_mfma_f32_16x16x32_bf16 v[186:189], v[182:185], v[16:19], v[36:39]
	v_mfma_f32_16x16x32_bf16 v[224:227], v[182:185], v[24:27], v[28:31]
	v_mfma_f32_16x16x32_bf16 v[228:231], v[182:185], v[32:35], v[20:23]
	v_mfma_f32_16x16x32_bf16 v[182:185], v[182:185], v[40:43], v[12:15]
	v_mfma_f32_16x16x32_bf16 v[232:235], v[178:181], v[16:19], v[8:11]
	v_mfma_f32_16x16x32_bf16 v[236:239], v[178:181], v[24:27], v[4:7]
	v_mfma_f32_16x16x32_bf16 v[240:243], v[178:181], v[32:35], v[0:3]
	v_mfma_f32_16x16x32_bf16 v[244:247], v[178:181], v[40:43], v[108:111]
	s_nop 1
	v_add_u32_e32 v0, v162, v150
	v_add_u32_e32 v144, v144, v150
	ds_read_b128 v[108:111], v0
	ds_read_b128 v[178:181], v0 offset:2048
	ds_read_b128 v[248:251], v0 offset:4096
	ds_read_b128 v[192:195], v0 offset:6144
	ds_read_b128 v[0:3], v144 offset:32768
	ds_read_b128 v[4:7], v144 offset:34816
	ds_read_b128 v[198:201], v144 offset:36864
	ds_read_b128 v[162:165], v144 offset:38912
	s_waitcnt lgkmcnt(0)
	v_mfma_f32_16x16x32_bf16 v[88:91], v[108:111], v[0:3], v[124:127]
	v_mfma_f32_16x16x32_bf16 v[96:99], v[108:111], v[4:7], v[120:123]
	v_mfma_f32_16x16x32_bf16 v[80:83], v[108:111], v[198:201], v[116:119]
	v_mfma_f32_16x16x32_bf16 v[84:87], v[108:111], v[162:165], v[112:115]
	v_mfma_f32_16x16x32_bf16 v[40:43], v[178:181], v[0:3], v[104:107]
	v_mfma_f32_16x16x32_bf16 v[52:55], v[178:181], v[4:7], v[208:211]
	v_mfma_f32_16x16x32_bf16 v[32:35], v[178:181], v[198:201], v[212:215]
	v_mfma_f32_16x16x32_bf16 v[36:39], v[178:181], v[162:165], v[216:219]
	v_mfma_f32_16x16x32_bf16 v[24:27], v[248:251], v[0:3], v[72:75]
	v_mfma_f32_16x16x32_bf16 v[28:31], v[248:251], v[4:7], v[64:67]
	v_mfma_f32_16x16x32_bf16 v[16:19], v[248:251], v[198:201], v[56:59]
	v_mfma_f32_16x16x32_bf16 v[20:23], v[248:251], v[162:165], v[48:51]
	v_mfma_f32_16x16x32_bf16 v[8:11], v[192:195], v[0:3], v[158:161]
	v_mfma_f32_16x16x32_bf16 v[12:15], v[192:195], v[4:7], v[152:155]
	v_mfma_f32_16x16x32_bf16 v[0:3], v[192:195], v[198:201], v[132:135]
	v_mfma_f32_16x16x32_bf16 v[4:7], v[192:195], v[162:165], v[128:131]
	ds_read_b128 v[48:51], v144 offset:40960
	ds_read_b128 v[64:67], v144 offset:43008
	s_nop 0
	ds_read_b128 v[128:131], v144 offset:45056
	ds_read_b128 v[132:135], v144 offset:47104
	s_waitcnt lgkmcnt(0)
	v_mfma_f32_16x16x32_bf16 v[104:107], v[178:181], v[48:51], v[68:71]
	v_cmp_ne_u32_e64 s[8:9], 0, v146
	v_cmp_eq_u32_e32 vcc, 0, v146
	s_waitcnt vmcnt(0)
	v_lshl_or_b32 v68, v148, 2, v149
	v_lshl_add_u32 v69, v147, 2, 0
	v_mfma_f32_16x16x32_bf16 v[120:123], v[108:111], v[48:51], v[100:103]
	s_barrier
	v_mfma_f32_16x16x32_bf16 v[124:127], v[108:111], v[64:67], v[92:95]
	v_mfma_f32_16x16x32_bf16 v[112:115], v[108:111], v[128:131], v[220:223]
	v_mfma_f32_16x16x32_bf16 v[116:119], v[108:111], v[132:135], v[76:79]
	v_mfma_f32_16x16x32_bf16 v[108:111], v[178:181], v[64:67], v[60:63]
	v_mfma_f32_16x16x32_bf16 v[92:95], v[178:181], v[128:131], v[204:207]
	v_mfma_f32_16x16x32_bf16 v[100:103], v[178:181], v[132:135], v[44:47]
	v_mfma_f32_16x16x32_bf16 v[56:59], v[248:251], v[48:51], v[186:189]
	v_mfma_f32_16x16x32_bf16 v[60:63], v[248:251], v[64:67], v[224:227]
	v_mfma_f32_16x16x32_bf16 v[44:47], v[248:251], v[128:131], v[228:231]
	v_mfma_f32_16x16x32_bf16 v[72:75], v[248:251], v[132:135], v[182:185]
	v_mfma_f32_16x16x32_bf16 v[48:51], v[192:195], v[48:51], v[232:235]
	s_nop 1
	v_lshl_add_u32 v182, v68, 9, v69
	v_add_u32_e32 v183, 0x400, v182
	v_add_u32_e32 v181, 0x2000, v182
	v_mfma_f32_16x16x32_bf16 v[64:67], v[192:195], v[64:67], v[236:239]
	v_add_u32_e32 v180, 0x2400, v182
	v_add_u32_e32 v179, 0x4000, v182
	v_add_u32_e32 v178, 0x4400, v182
	v_mfma_f32_16x16x32_bf16 v[68:71], v[192:195], v[128:131], v[240:243]
	v_add_u32_e32 v175, 0x6000, v182
	v_add_u32_e32 v174, 0x6400, v182
	v_mfma_f32_16x16x32_bf16 v[76:79], v[192:195], v[132:135], v[244:247]
	s_and_saveexec_b64 s[0:1], vcc
	s_cbranch_execz .LBB0_215
	ds_write2_b32 v182, v88, v96 offset1:16
	ds_write2_b32 v182, v89, v97 offset0:128 offset1:144
	ds_write2_b32 v183, v90, v98 offset1:16
	ds_write2_b32 v183, v91, v99 offset0:128 offset1:144
	ds_write2_b32 v182, v80, v84 offset0:32 offset1:48
	ds_write2_b32 v182, v81, v85 offset0:160 offset1:176
	ds_write2_b32 v183, v82, v86 offset0:32 offset1:48
	ds_write2_b32 v183, v83, v87 offset0:160 offset1:176
	ds_write2_b32 v182, v120, v124 offset0:64 offset1:80
	ds_write2_b32 v182, v121, v125 offset0:192 offset1:208
	ds_write2_b32 v183, v122, v126 offset0:64 offset1:80
	ds_write2_b32 v183, v123, v127 offset0:192 offset1:208
	ds_write2_b32 v182, v112, v116 offset0:96 offset1:112
	ds_write2_b32 v182, v113, v117 offset0:224 offset1:240
	ds_write2_b32 v183, v114, v118 offset0:96 offset1:112
	ds_write2_b32 v183, v115, v119 offset0:224 offset1:240
	ds_write2_b32 v181, v40, v52 offset1:16
	ds_write2_b32 v181, v41, v53 offset0:128 offset1:144
	ds_write2_b32 v180, v42, v54 offset1:16
	ds_write2_b32 v180, v43, v55 offset0:128 offset1:144
	ds_write2_b32 v181, v32, v36 offset0:32 offset1:48
	ds_write2_b32 v181, v33, v37 offset0:160 offset1:176
	ds_write2_b32 v180, v34, v38 offset0:32 offset1:48
	ds_write2_b32 v180, v35, v39 offset0:160 offset1:176
	ds_write2_b32 v181, v104, v108 offset0:64 offset1:80
	ds_write2_b32 v181, v105, v109 offset0:192 offset1:208
	ds_write2_b32 v180, v106, v110 offset0:64 offset1:80
	ds_write2_b32 v180, v107, v111 offset0:192 offset1:208
	ds_write2_b32 v181, v92, v100 offset0:96 offset1:112
	ds_write2_b32 v181, v93, v101 offset0:224 offset1:240
	ds_write2_b32 v180, v94, v102 offset0:96 offset1:112
	ds_write2_b32 v180, v95, v103 offset0:224 offset1:240
	ds_write2_b32 v179, v24, v28 offset1:16
	ds_write2_b32 v179, v25, v29 offset0:128 offset1:144
	ds_write2_b32 v178, v26, v30 offset1:16
	ds_write2_b32 v178, v27, v31 offset0:128 offset1:144
	ds_write2_b32 v179, v16, v20 offset0:32 offset1:48
	ds_write2_b32 v179, v17, v21 offset0:160 offset1:176
	ds_write2_b32 v178, v18, v22 offset0:32 offset1:48
	ds_write2_b32 v178, v19, v23 offset0:160 offset1:176
	ds_write2_b32 v179, v56, v60 offset0:64 offset1:80
	ds_write2_b32 v179, v57, v61 offset0:192 offset1:208
	ds_write2_b32 v178, v58, v62 offset0:64 offset1:80
	ds_write2_b32 v178, v59, v63 offset0:192 offset1:208
	ds_write2_b32 v179, v44, v72 offset0:96 offset1:112
	ds_write2_b32 v179, v45, v73 offset0:224 offset1:240
	ds_write2_b32 v178, v46, v74 offset0:96 offset1:112
	ds_write2_b32 v178, v47, v75 offset0:224 offset1:240
	ds_write2_b32 v175, v8, v12 offset1:16
	ds_write2_b32 v175, v9, v13 offset0:128 offset1:144
	ds_write2_b32 v174, v10, v14 offset1:16
	ds_write2_b32 v174, v11, v15 offset0:128 offset1:144
	ds_write2_b32 v175, v0, v4 offset0:32 offset1:48
	ds_write2_b32 v175, v1, v5 offset0:160 offset1:176
	ds_write2_b32 v174, v2, v6 offset0:32 offset1:48
	ds_write2_b32 v174, v3, v7 offset0:160 offset1:176
	ds_write2_b32 v175, v48, v64 offset0:64 offset1:80
	ds_write2_b32 v175, v49, v65 offset0:192 offset1:208
	ds_write2_b32 v174, v50, v66 offset0:64 offset1:80
	ds_write2_b32 v174, v51, v67 offset0:192 offset1:208
	ds_write2_b32 v175, v68, v76 offset0:96 offset1:112
	ds_write2_b32 v175, v69, v77 offset0:224 offset1:240
	ds_write2_b32 v174, v70, v78 offset0:96 offset1:112
	ds_write2_b32 v174, v71, v79 offset0:224 offset1:240

.LBB0_659:
	s_add_i32 s1, s0, 0x10000
	s_and_b32 s11, s1, 0x10000
	s_waitcnt vmcnt(0)
	s_barrier
	s_and_b32 s0, s0, 0x10000
	s_add_i32 s0, s0, 0
	v_add_u32_e32 v151, s0, v149
	v_add_u32_e32 v164, v151, v147
	ds_read_b128 v[152:155], v164
	ds_read_b128 v[156:159], v164 offset:2048
	ds_read_b128 v[160:163], v164 offset:4096
	ds_read_b128 v[164:167], v164 offset:6144
	v_add_u32_e32 v251, v151, v146
	v_add_u32_e32 v176, s0, v148
	v_add_u32_e32 v186, v176, v147
	ds_read_b128 v[168:171], v186 offset:32768
	ds_read_b128 v[172:175], v186 offset:34816
	ds_read_b128 v[178:181], v186 offset:36864
	ds_read_b128 v[182:185], v186 offset:38912
	v_add_u32_e32 v250, v176, v146
	v_add_u32_e32 v254, s11, v150
	v_add_u32_e32 v228, 0x2000, v254
	v_readfirstlane_b32 s11, v254
	v_lshl_add_u64 v[188:189], v[128:129], 0, s[2:3]
	s_mov_b32 m0, s11
	v_readfirstlane_b32 s11, v228
	v_add_u32_e32 v228, 0x4000, v254
	global_load_lds_dwordx4 v[188:189], off
	v_lshl_add_u64 v[188:189], v[130:131], 0, s[2:3]
	s_mov_b32 m0, s11
	s_waitcnt lgkmcnt(0)
	v_mfma_f32_16x16x32_bf16 v[124:127], v[152:155], v[168:171], v[124:127]
	ds_read_b128 v[212:215], v186 offset:40960
	v_mfma_f32_16x16x32_bf16 v[120:123], v[152:155], v[172:175], v[120:123]
	ds_read_b128 v[216:219], v186 offset:43008
	v_readfirstlane_b32 s11, v228
	v_add_u32_e32 v228, 0x6000, v254
	v_mfma_f32_16x16x32_bf16 v[116:119], v[152:155], v[178:181], v[116:119]
	ds_read_b128 v[220:223], v186 offset:45056
	global_load_lds_dwordx4 v[188:189], off
	v_lshl_add_u64 v[188:189], v[132:133], 0, s[2:3]
	v_mfma_f32_16x16x32_bf16 v[112:115], v[152:155], v[182:185], v[112:115]
	ds_read_b128 v[224:227], v186 offset:47104
	s_mov_b32 m0, s11
	v_readfirstlane_b32 s11, v228
	v_mfma_f32_16x16x32_bf16 v[104:107], v[156:159], v[168:171], v[104:107]
	global_load_lds_dwordx4 v[188:189], off
	v_lshl_add_u64 v[188:189], v[134:135], 0, s[2:3]
	v_mfma_f32_16x16x32_bf16 v[96:99], v[156:159], v[172:175], v[96:99]
	s_mov_b32 m0, s11
	v_add_u32_e32 v253, 0x8000, v254
	v_mfma_f32_16x16x32_bf16 v[88:91], v[156:159], v[178:181], v[88:91]
	global_load_lds_dwordx4 v[188:189], off
	v_lshl_add_u64 v[188:189], v[136:137], 0, s[2:3]
	v_mfma_f32_16x16x32_bf16 v[80:83], v[156:159], v[182:185], v[80:83]
	s_mov_b64 s[18:19], 0x550080
	v_readfirstlane_b32 s11, v253
	v_mfma_f32_16x16x32_bf16 v[72:75], v[160:163], v[168:171], v[72:75]
	v_add_u32_e32 v253, 0xa000, v254
	v_lshl_add_u64 v[228:229], v[188:189], 0, s[18:19]
	v_mfma_f32_16x16x32_bf16 v[64:67], v[160:163], v[172:175], v[64:67]
	s_mov_b32 m0, s11
	s_mov_b64 s[18:19], 0x572080
	v_mfma_f32_16x16x32_bf16 v[56:59], v[160:163], v[178:181], v[56:59]
	v_readfirstlane_b32 s11, v253
	v_add_u32_e32 v253, 0xc000, v254
	v_mfma_f32_16x16x32_bf16 v[48:51], v[160:163], v[182:185], v[48:51]
	global_load_lds_dwordx4 v[228:229], off
	v_lshl_add_u64 v[228:229], v[188:189], 0, s[18:19]
	v_mfma_f32_16x16x32_bf16 v[40:43], v[164:167], v[168:171], v[40:43]
	s_mov_b32 m0, s11
	s_mov_b64 s[18:19], 0x594080
	v_mfma_f32_16x16x32_bf16 v[32:35], v[164:167], v[172:175], v[32:35]
	v_readfirstlane_b32 s11, v253
	v_add_u32_e32 v254, 0xe000, v254
	v_mfma_f32_16x16x32_bf16 v[24:27], v[164:167], v[178:181], v[24:27]
	global_load_lds_dwordx4 v[228:229], off
	v_lshl_add_u64 v[228:229], v[188:189], 0, s[18:19]
	v_mfma_f32_16x16x32_bf16 v[16:19], v[164:167], v[182:185], v[16:19]
	s_mov_b32 m0, s11
	s_mov_b64 s[18:19], 0x5b6080
	s_waitcnt lgkmcnt(0)
	v_mfma_f32_16x16x32_bf16 v[100:103], v[152:155], v[212:215], v[100:103]
	ds_read_b128 v[192:195], v251
	v_readfirstlane_b32 s11, v254
	global_load_lds_dwordx4 v[228:229], off
	v_mfma_f32_16x16x32_bf16 v[92:95], v[152:155], v[216:219], v[92:95]
	ds_read_b128 v[198:201], v251 offset:2048
	v_lshl_add_u64 v[188:189], v[188:189], 0, s[18:19]
	s_mov_b32 m0, s11
	v_mfma_f32_16x16x32_bf16 v[84:87], v[152:155], v[220:223], v[84:87]
	ds_read_b128 v[204:207], v251 offset:4096
	global_load_lds_dwordx4 v[188:189], off
	v_mfma_f32_16x16x32_bf16 v[76:79], v[152:155], v[224:227], v[76:79]
	ds_read_b128 v[208:211], v251 offset:6144
	v_mfma_f32_16x16x32_bf16 v[68:71], v[156:159], v[212:215], v[68:71]
	v_mfma_f32_16x16x32_bf16 v[60:63], v[156:159], v[216:219], v[60:63]
	v_mfma_f32_16x16x32_bf16 v[52:55], v[156:159], v[220:223], v[52:55]
	ds_read_b128 v[168:171], v250 offset:32768
	v_mfma_f32_16x16x32_bf16 v[44:47], v[156:159], v[224:227], v[44:47]
	ds_read_b128 v[172:175], v250 offset:34816
	v_mfma_f32_16x16x32_bf16 v[36:39], v[160:163], v[212:215], v[36:39]
	ds_read_b128 v[178:181], v250 offset:36864
	v_mfma_f32_16x16x32_bf16 v[28:31], v[160:163], v[216:219], v[28:31]
	ds_read_b128 v[182:185], v250 offset:38912
	v_mfma_f32_16x16x32_bf16 v[20:23], v[160:163], v[220:223], v[20:23]
	v_mfma_f32_16x16x32_bf16 v[12:15], v[160:163], v[224:227], v[12:15]
	v_mfma_f32_16x16x32_bf16 v[8:11], v[164:167], v[212:215], v[8:11]
	v_mfma_f32_16x16x32_bf16 v[4:7], v[164:167], v[216:219], v[4:7]
	v_mfma_f32_16x16x32_bf16 v[0:3], v[164:167], v[220:223], v[0:3]
	v_mfma_f32_16x16x32_bf16 v[108:111], v[164:167], v[224:227], v[108:111]
	s_waitcnt lgkmcnt(0)
	v_mfma_f32_16x16x32_bf16 v[124:127], v[192:195], v[168:171], v[124:127]
	ds_read_b128 v[212:215], v250 offset:40960
	v_mfma_f32_16x16x32_bf16 v[120:123], v[192:195], v[172:175], v[120:123]
	ds_read_b128 v[216:219], v250 offset:43008
	v_mfma_f32_16x16x32_bf16 v[116:119], v[192:195], v[178:181], v[116:119]
	ds_read_b128 v[220:223], v250 offset:45056
	v_mfma_f32_16x16x32_bf16 v[112:115], v[192:195], v[182:185], v[112:115]
	ds_read_b128 v[224:227], v250 offset:47104
	v_mfma_f32_16x16x32_bf16 v[104:107], v[198:201], v[168:171], v[104:107]
	v_mfma_f32_16x16x32_bf16 v[96:99], v[198:201], v[172:175], v[96:99]
	v_mfma_f32_16x16x32_bf16 v[88:91], v[198:201], v[178:181], v[88:91]
	v_mfma_f32_16x16x32_bf16 v[80:83], v[198:201], v[182:185], v[80:83]
	v_mfma_f32_16x16x32_bf16 v[72:75], v[204:207], v[168:171], v[72:75]
	v_mfma_f32_16x16x32_bf16 v[64:67], v[204:207], v[172:175], v[64:67]
	v_mfma_f32_16x16x32_bf16 v[56:59], v[204:207], v[178:181], v[56:59]
	v_mfma_f32_16x16x32_bf16 v[48:51], v[204:207], v[182:185], v[48:51]
	v_mfma_f32_16x16x32_bf16 v[40:43], v[208:211], v[168:171], v[40:43]
	v_mfma_f32_16x16x32_bf16 v[32:35], v[208:211], v[172:175], v[32:35]
	v_mfma_f32_16x16x32_bf16 v[24:27], v[208:211], v[178:181], v[24:27]
	v_mfma_f32_16x16x32_bf16 v[16:19], v[208:211], v[182:185], v[16:19]
	s_waitcnt lgkmcnt(0)
	v_mfma_f32_16x16x32_bf16 v[100:103], v[192:195], v[212:215], v[100:103]
	v_mfma_f32_16x16x32_bf16 v[92:95], v[192:195], v[216:219], v[92:95]
	v_mfma_f32_16x16x32_bf16 v[84:87], v[192:195], v[220:223], v[84:87]
	v_mfma_f32_16x16x32_bf16 v[76:79], v[192:195], v[224:227], v[76:79]
	v_mfma_f32_16x16x32_bf16 v[68:71], v[198:201], v[212:215], v[68:71]
	v_mfma_f32_16x16x32_bf16 v[60:63], v[198:201], v[216:219], v[60:63]
	v_mfma_f32_16x16x32_bf16 v[52:55], v[198:201], v[220:223], v[52:55]
	v_mfma_f32_16x16x32_bf16 v[44:47], v[198:201], v[224:227], v[44:47]
	v_mfma_f32_16x16x32_bf16 v[36:39], v[204:207], v[212:215], v[36:39]
	v_mfma_f32_16x16x32_bf16 v[28:31], v[204:207], v[216:219], v[28:31]
	v_mfma_f32_16x16x32_bf16 v[20:23], v[204:207], v[220:223], v[20:23]
	v_mfma_f32_16x16x32_bf16 v[12:15], v[204:207], v[224:227], v[12:15]
	s_add_u32 s2, s2, 0x80
	s_addc_u32 s3, s3, 0
	s_cmpk_eq_i32 s2, 0x780
	s_mov_b32 s0, s1
	v_mfma_f32_16x16x32_bf16 v[8:11], v[208:211], v[212:215], v[8:11]
	v_mfma_f32_16x16x32_bf16 v[4:7], v[208:211], v[216:219], v[4:7]
	v_mfma_f32_16x16x32_bf16 v[0:3], v[208:211], v[220:223], v[0:3]
	v_mfma_f32_16x16x32_bf16 v[108:111], v[208:211], v[224:227], v[108:111]
	s_cbranch_scc0 .LBB0_659
	s_add_i32 s0, 0, 0x10000
	v_add_u32_e32 v136, s0, v149
	v_add_u32_e32 v137, v136, v147
	s_waitcnt vmcnt(0)
	s_barrier
	ds_read_b128 v[128:131], v137
	ds_read_b128 v[132:135], v137 offset:2048
	ds_read_b128 v[150:153], v137 offset:4096
	ds_read_b128 v[154:157], v137 offset:6144
	v_add_u32_e32 v137, s0, v148
	v_add_u32_e32 v147, v137, v147
	ds_read_b128 v[158:161], v147 offset:32768
	ds_read_b128 v[162:165], v147 offset:34816
	ds_read_b128 v[166:169], v147 offset:36864
	ds_read_b128 v[170:173], v147 offset:38912
	s_waitcnt lgkmcnt(0)
	v_mfma_f32_16x16x32_bf16 v[124:127], v[128:131], v[158:161], v[124:127]
	v_mfma_f32_16x16x32_bf16 v[120:123], v[128:131], v[162:165], v[120:123]
	v_mfma_f32_16x16x32_bf16 v[116:119], v[128:131], v[166:169], v[116:119]
	v_mfma_f32_16x16x32_bf16 v[112:115], v[128:131], v[170:173], v[112:115]
	v_mfma_f32_16x16x32_bf16 v[104:107], v[132:135], v[158:161], v[104:107]
	v_mfma_f32_16x16x32_bf16 v[72:75], v[150:153], v[158:161], v[72:75]
	v_mfma_f32_16x16x32_bf16 v[64:67], v[150:153], v[162:165], v[64:67]
	v_mfma_f32_16x16x32_bf16 v[56:59], v[150:153], v[166:169], v[56:59]
	v_mfma_f32_16x16x32_bf16 v[48:51], v[150:153], v[170:173], v[48:51]
	v_mfma_f32_16x16x32_bf16 v[178:181], v[132:135], v[162:165], v[96:99]
	v_mfma_f32_16x16x32_bf16 v[182:185], v[132:135], v[166:169], v[88:91]
	v_mfma_f32_16x16x32_bf16 v[186:189], v[132:135], v[170:173], v[80:83]
	v_mfma_f32_16x16x32_bf16 v[158:161], v[154:157], v[158:161], v[40:43]
	v_mfma_f32_16x16x32_bf16 v[162:165], v[154:157], v[162:165], v[32:35]
	v_mfma_f32_16x16x32_bf16 v[166:169], v[154:157], v[166:169], v[24:27]
	v_mfma_f32_16x16x32_bf16 v[170:173], v[154:157], v[170:173], v[16:19]
	s_nop 2
	ds_read_b128 v[16:19], v147 offset:40960
	ds_read_b128 v[24:27], v147 offset:43008
	ds_read_b128 v[32:35], v147 offset:45056
	ds_read_b128 v[40:43], v147 offset:47104
	s_waitcnt lgkmcnt(0)
	v_mfma_f32_16x16x32_bf16 v[100:103], v[128:131], v[16:19], v[100:103]
	v_mfma_f32_16x16x32_bf16 v[92:95], v[128:131], v[24:27], v[92:95]
	v_mfma_f32_16x16x32_bf16 v[192:195], v[128:131], v[32:35], v[84:87]
	v_mfma_f32_16x16x32_bf16 v[76:79], v[128:131], v[40:43], v[76:79]
	v_mfma_f32_16x16x32_bf16 v[68:71], v[132:135], v[16:19], v[68:71]
	v_mfma_f32_16x16x32_bf16 v[60:63], v[132:135], v[24:27], v[60:63]
	v_mfma_f32_16x16x32_bf16 v[128:131], v[132:135], v[32:35], v[52:55]
	v_mfma_f32_16x16x32_bf16 v[44:47], v[132:135], v[40:43], v[44:47]
	v_mfma_f32_16x16x32_bf16 v[132:135], v[150:153], v[16:19], v[36:39]
	v_mfma_f32_16x16x32_bf16 v[198:201], v[150:153], v[24:27], v[28:31]
	v_mfma_f32_16x16x32_bf16 v[204:207], v[150:153], v[32:35], v[20:23]
	v_mfma_f32_16x16x32_bf16 v[148:151], v[150:153], v[40:43], v[12:15]
	v_mfma_f32_16x16x32_bf16 v[208:211], v[154:157], v[16:19], v[8:11]
	v_mfma_f32_16x16x32_bf16 v[212:215], v[154:157], v[24:27], v[4:7]
	v_mfma_f32_16x16x32_bf16 v[216:219], v[154:157], v[32:35], v[0:3]
	v_mfma_f32_16x16x32_bf16 v[154:157], v[154:157], v[40:43], v[108:111]
	s_nop 1
	v_add_u32_e32 v0, v136, v146
	v_add_u32_e32 v136, v137, v146
	ds_read_b128 v[108:111], v0
	ds_read_b128 v[220:223], v0 offset:2048
	ds_read_b128 v[224:227], v0 offset:4096
	ds_read_b128 v[228:231], v0 offset:6144
	ds_read_b128 v[0:3], v136 offset:32768
	ds_read_b128 v[4:7], v136 offset:34816
	ds_read_b128 v[232:235], v136 offset:36864
	ds_read_b128 v[236:239], v136 offset:38912
	s_waitcnt lgkmcnt(0)
	v_mfma_f32_16x16x32_bf16 v[88:91], v[108:111], v[0:3], v[124:127]
	v_mfma_f32_16x16x32_bf16 v[96:99], v[108:111], v[4:7], v[120:123]
	v_mfma_f32_16x16x32_bf16 v[80:83], v[108:111], v[232:235], v[116:119]
	v_mfma_f32_16x16x32_bf16 v[84:87], v[108:111], v[236:239], v[112:115]
	v_mfma_f32_16x16x32_bf16 v[40:43], v[220:223], v[0:3], v[104:107]
	v_mfma_f32_16x16x32_bf16 v[52:55], v[220:223], v[4:7], v[178:181]
	v_mfma_f32_16x16x32_bf16 v[32:35], v[220:223], v[232:235], v[182:185]
	v_mfma_f32_16x16x32_bf16 v[36:39], v[220:223], v[236:239], v[186:189]
	v_mfma_f32_16x16x32_bf16 v[24:27], v[224:227], v[0:3], v[72:75]
	v_mfma_f32_16x16x32_bf16 v[28:31], v[224:227], v[4:7], v[64:67]
	v_mfma_f32_16x16x32_bf16 v[16:19], v[224:227], v[232:235], v[56:59]
	v_mfma_f32_16x16x32_bf16 v[20:23], v[224:227], v[236:239], v[48:51]
	v_mfma_f32_16x16x32_bf16 v[8:11], v[228:231], v[0:3], v[158:161]
	v_mfma_f32_16x16x32_bf16 v[12:15], v[228:231], v[4:7], v[162:165]
	v_mfma_f32_16x16x32_bf16 v[0:3], v[228:231], v[232:235], v[166:169]
	v_mfma_f32_16x16x32_bf16 v[4:7], v[228:231], v[236:239], v[170:173]
	ds_read_b128 v[48:51], v136 offset:40960
	ds_read_b128 v[64:67], v136 offset:43008
	ds_read_b128 v[158:161], v136 offset:45056
	ds_read_b128 v[162:165], v136 offset:47104
	s_waitcnt lgkmcnt(0)
	v_mfma_f32_16x16x32_bf16 v[104:107], v[220:223], v[48:51], v[68:71]
	v_cmp_ne_u32_e32 vcc, 0, v138
	v_cmp_eq_u32_e64 s[2:3], 0, v138
	s_waitcnt vmcnt(0)
	v_lshl_or_b32 v68, v140, 2, v141
	v_lshl_add_u32 v69, v139, 2, 0
	v_mfma_f32_16x16x32_bf16 v[120:123], v[108:111], v[48:51], v[100:103]
	v_lshl_add_u32 v152, v68, 9, v69
	v_add_u32_e32 v153, 0x400, v152
	v_add_u32_e32 v147, 0x6000, v152
	v_mfma_f32_16x16x32_bf16 v[124:127], v[108:111], v[64:67], v[92:95]
	v_add_u32_e32 v146, 0x6400, v152
	s_barrier
	v_mfma_f32_16x16x32_bf16 v[112:115], v[108:111], v[158:161], v[192:195]
	v_mfma_f32_16x16x32_bf16 v[116:119], v[108:111], v[162:165], v[76:79]
	v_mfma_f32_16x16x32_bf16 v[108:111], v[220:223], v[64:67], v[60:63]
	v_mfma_f32_16x16x32_bf16 v[92:95], v[220:223], v[158:161], v[128:131]
	v_mfma_f32_16x16x32_bf16 v[100:103], v[220:223], v[162:165], v[44:47]
	v_mfma_f32_16x16x32_bf16 v[56:59], v[224:227], v[48:51], v[132:135]
	v_mfma_f32_16x16x32_bf16 v[60:63], v[224:227], v[64:67], v[198:201]
	v_mfma_f32_16x16x32_bf16 v[44:47], v[224:227], v[158:161], v[204:207]
	v_mfma_f32_16x16x32_bf16 v[72:75], v[224:227], v[162:165], v[148:151]
	v_mfma_f32_16x16x32_bf16 v[48:51], v[228:231], v[48:51], v[208:211]
	s_nop 1
	v_add_u32_e32 v151, 0x2000, v152
	v_add_u32_e32 v150, 0x2400, v152
	v_add_u32_e32 v149, 0x4000, v152
	v_mfma_f32_16x16x32_bf16 v[64:67], v[228:231], v[64:67], v[212:215]
	v_add_u32_e32 v148, 0x4400, v152
	v_mfma_f32_16x16x32_bf16 v[68:71], v[228:231], v[158:161], v[216:219]
	v_mfma_f32_16x16x32_bf16 v[76:79], v[228:231], v[162:165], v[154:157]
	s_and_saveexec_b64 s[0:1], s[2:3]
	s_cbranch_execz .LBB0_662
	ds_write2_b32 v152, v88, v96 offset1:16
	ds_write2_b32 v152, v89, v97 offset0:128 offset1:144
	ds_write2_b32 v153, v90, v98 offset1:16
	ds_write2_b32 v153, v91, v99 offset0:128 offset1:144
	ds_write2_b32 v152, v80, v84 offset0:32 offset1:48
	ds_write2_b32 v152, v81, v85 offset0:160 offset1:176
	ds_write2_b32 v153, v82, v86 offset0:32 offset1:48
	ds_write2_b32 v153, v83, v87 offset0:160 offset1:176
	ds_write2_b32 v152, v120, v124 offset0:64 offset1:80
	ds_write2_b32 v152, v121, v125 offset0:192 offset1:208
	ds_write2_b32 v153, v122, v126 offset0:64 offset1:80
	ds_write2_b32 v153, v123, v127 offset0:192 offset1:208
	ds_write2_b32 v152, v112, v116 offset0:96 offset1:112
	ds_write2_b32 v152, v113, v117 offset0:224 offset1:240
	ds_write2_b32 v153, v114, v118 offset0:96 offset1:112
	ds_write2_b32 v153, v115, v119 offset0:224 offset1:240
	ds_write2_b32 v151, v40, v52 offset1:16
	ds_write2_b32 v151, v41, v53 offset0:128 offset1:144
	ds_write2_b32 v150, v42, v54 offset1:16
	ds_write2_b32 v150, v43, v55 offset0:128 offset1:144
	ds_write2_b32 v151, v32, v36 offset0:32 offset1:48
	ds_write2_b32 v151, v33, v37 offset0:160 offset1:176
	ds_write2_b32 v150, v34, v38 offset0:32 offset1:48
	ds_write2_b32 v150, v35, v39 offset0:160 offset1:176
	ds_write2_b32 v151, v104, v108 offset0:64 offset1:80
	ds_write2_b32 v151, v105, v109 offset0:192 offset1:208
	ds_write2_b32 v150, v106, v110 offset0:64 offset1:80
	ds_write2_b32 v150, v107, v111 offset0:192 offset1:208
	ds_write2_b32 v151, v92, v100 offset0:96 offset1:112
	ds_write2_b32 v151, v93, v101 offset0:224 offset1:240
	ds_write2_b32 v150, v94, v102 offset0:96 offset1:112
	ds_write2_b32 v150, v95, v103 offset0:224 offset1:240
	ds_write2_b32 v149, v24, v28 offset1:16
	ds_write2_b32 v149, v25, v29 offset0:128 offset1:144
	ds_write2_b32 v148, v26, v30 offset1:16
	ds_write2_b32 v148, v27, v31 offset0:128 offset1:144
	ds_write2_b32 v149, v16, v20 offset0:32 offset1:48
	ds_write2_b32 v149, v17, v21 offset0:160 offset1:176
	ds_write2_b32 v148, v18, v22 offset0:32 offset1:48
	ds_write2_b32 v148, v19, v23 offset0:160 offset1:176
	ds_write2_b32 v149, v56, v60 offset0:64 offset1:80
	ds_write2_b32 v149, v57, v61 offset0:192 offset1:208
	ds_write2_b32 v148, v58, v62 offset0:64 offset1:80
	ds_write2_b32 v148, v59, v63 offset0:192 offset1:208
	ds_write2_b32 v149, v44, v72 offset0:96 offset1:112
	ds_write2_b32 v149, v45, v73 offset0:224 offset1:240
	ds_write2_b32 v148, v46, v74 offset0:96 offset1:112
	ds_write2_b32 v148, v47, v75 offset0:224 offset1:240
	ds_write2_b32 v147, v8, v12 offset1:16
	ds_write2_b32 v147, v9, v13 offset0:128 offset1:144
	ds_write2_b32 v146, v10, v14 offset1:16
	ds_write2_b32 v146, v11, v15 offset0:128 offset1:144
	ds_write2_b32 v147, v0, v4 offset0:32 offset1:48
	ds_write2_b32 v147, v1, v5 offset0:160 offset1:176
	ds_write2_b32 v146, v2, v6 offset0:32 offset1:48
	ds_write2_b32 v146, v3, v7 offset0:160 offset1:176
	ds_write2_b32 v147, v48, v64 offset0:64 offset1:80
	ds_write2_b32 v147, v49, v65 offset0:192 offset1:208
	ds_write2_b32 v146, v50, v66 offset0:64 offset1:80
	ds_write2_b32 v146, v51, v67 offset0:192 offset1:208
	ds_write2_b32 v147, v68, v76 offset0:96 offset1:112
	ds_write2_b32 v147, v69, v77 offset0:224 offset1:240
	ds_write2_b32 v146, v70, v78 offset0:96 offset1:112
	ds_write2_b32 v146, v71, v79 offset0:224 offset1:240

.LBB0_1074:
	s_add_i32 s5, s4, 0x10000
	s_and_b32 s40, s5, 0x10000
	s_waitcnt vmcnt(0)
	s_barrier
	s_and_b32 s4, s4, 0x10000
	s_add_i32 s4, s4, 0
	v_add_u32_e32 v147, s4, v144
	v_add_u32_e32 v160, v147, v143
	ds_read_b128 v[148:151], v160
	ds_read_b128 v[152:155], v160 offset:2048
	ds_read_b128 v[156:159], v160 offset:4096
	ds_read_b128 v[170:173], v160 offset:6144
	v_add_u32_e32 v251, v147, v142
	v_add_u32_e32 v160, s4, v145
	v_add_u32_e32 v161, v160, v143
	ds_read_b128 v[178:181], v161 offset:32768
	ds_read_b128 v[182:185], v161 offset:34816
	ds_read_b128 v[186:189], v161 offset:36864
	ds_read_b128 v[192:195], v161 offset:38912
	v_add_u32_e32 v250, v160, v142
	v_add_u32_e32 v254, s40, v146
	v_add_u32_e32 v232, 0x2000, v254
	v_readfirstlane_b32 s40, v254
	v_lshl_add_u64 v[174:175], v[136:137], 0, s[2:3]
	s_mov_b32 m0, s40
	v_readfirstlane_b32 s40, v232
	v_add_u32_e32 v232, 0x4000, v254
	global_load_lds_dwordx4 v[174:175], off
	v_lshl_add_u64 v[174:175], v[134:135], 0, s[2:3]
	s_mov_b32 m0, s40
	s_waitcnt lgkmcnt(0)
	v_mfma_f32_16x16x32_bf16 v[124:127], v[148:151], v[178:181], v[124:127]
	ds_read_b128 v[216:219], v161 offset:40960
	v_mfma_f32_16x16x32_bf16 v[120:123], v[148:151], v[182:185], v[120:123]
	ds_read_b128 v[220:223], v161 offset:43008
	v_readfirstlane_b32 s40, v232
	v_add_u32_e32 v232, 0x6000, v254
	v_mfma_f32_16x16x32_bf16 v[116:119], v[148:151], v[186:189], v[116:119]
	ds_read_b128 v[224:227], v161 offset:45056
	global_load_lds_dwordx4 v[174:175], off
	v_lshl_add_u64 v[174:175], v[132:133], 0, s[2:3]
	v_mfma_f32_16x16x32_bf16 v[112:115], v[148:151], v[192:195], v[112:115]
	ds_read_b128 v[228:231], v161 offset:47104
	s_mov_b32 m0, s40
	v_readfirstlane_b32 s40, v232
	v_mfma_f32_16x16x32_bf16 v[104:107], v[152:155], v[178:181], v[104:107]
	global_load_lds_dwordx4 v[174:175], off
	v_lshl_add_u64 v[174:175], v[130:131], 0, s[2:3]
	v_mfma_f32_16x16x32_bf16 v[96:99], v[152:155], v[182:185], v[96:99]
	s_mov_b32 m0, s40
	s_mov_b64 s[40:41], 0x770080
	v_mfma_f32_16x16x32_bf16 v[88:91], v[152:155], v[186:189], v[88:91]
	global_load_lds_dwordx4 v[174:175], off
	v_lshl_add_u64 v[174:175], v[128:129], 0, s[2:3]
	v_mfma_f32_16x16x32_bf16 v[80:83], v[152:155], v[192:195], v[80:83]
	v_add_u32_e32 v253, 0x8000, v254
	v_lshl_add_u64 v[232:233], v[174:175], 0, s[40:41]
	v_mfma_f32_16x16x32_bf16 v[72:75], v[156:159], v[178:181], v[72:75]
	v_readfirstlane_b32 s40, v253
	s_mov_b32 m0, s40
	v_mfma_f32_16x16x32_bf16 v[64:67], v[156:159], v[182:185], v[64:67]
	s_mov_b64 s[40:41], 0x792080
	v_add_u32_e32 v253, 0xa000, v254
	v_mfma_f32_16x16x32_bf16 v[56:59], v[156:159], v[186:189], v[56:59]
	global_load_lds_dwordx4 v[232:233], off
	v_lshl_add_u64 v[232:233], v[174:175], 0, s[40:41]
	v_mfma_f32_16x16x32_bf16 v[48:51], v[156:159], v[192:195], v[48:51]
	v_readfirstlane_b32 s40, v253
	s_mov_b32 m0, s40
	v_mfma_f32_16x16x32_bf16 v[40:43], v[170:173], v[178:181], v[40:43]
	s_mov_b64 s[40:41], 0x7b4080
	v_add_u32_e32 v253, 0xc000, v254
	v_mfma_f32_16x16x32_bf16 v[32:35], v[170:173], v[182:185], v[32:35]
	global_load_lds_dwordx4 v[232:233], off
	v_lshl_add_u64 v[232:233], v[174:175], 0, s[40:41]
	v_mfma_f32_16x16x32_bf16 v[24:27], v[170:173], v[186:189], v[24:27]
	v_readfirstlane_b32 s40, v253
	s_mov_b32 m0, s40
	v_mfma_f32_16x16x32_bf16 v[16:19], v[170:173], v[192:195], v[16:19]
	s_mov_b64 s[40:41], 0x7d6080
	v_add_u32_e32 v254, 0xe000, v254
	s_waitcnt lgkmcnt(0)
	v_mfma_f32_16x16x32_bf16 v[100:103], v[148:151], v[216:219], v[100:103]
	ds_read_b128 v[198:201], v251
	v_lshl_add_u64 v[174:175], v[174:175], 0, s[40:41]
	v_readfirstlane_b32 s40, v254
	v_mfma_f32_16x16x32_bf16 v[92:95], v[148:151], v[220:223], v[92:95]
	ds_read_b128 v[204:207], v251 offset:2048
	global_load_lds_dwordx4 v[232:233], off
	s_mov_b32 m0, s40
	v_mfma_f32_16x16x32_bf16 v[84:87], v[148:151], v[224:227], v[84:87]
	ds_read_b128 v[208:211], v251 offset:4096
	global_load_lds_dwordx4 v[174:175], off
	v_mfma_f32_16x16x32_bf16 v[76:79], v[148:151], v[228:231], v[76:79]
	ds_read_b128 v[212:215], v251 offset:6144
	v_mfma_f32_16x16x32_bf16 v[68:71], v[152:155], v[216:219], v[68:71]
	v_mfma_f32_16x16x32_bf16 v[60:63], v[152:155], v[220:223], v[60:63]
	v_mfma_f32_16x16x32_bf16 v[52:55], v[152:155], v[224:227], v[52:55]
	ds_read_b128 v[178:181], v250 offset:32768
	v_mfma_f32_16x16x32_bf16 v[44:47], v[152:155], v[228:231], v[44:47]
	ds_read_b128 v[182:185], v250 offset:34816
	v_mfma_f32_16x16x32_bf16 v[36:39], v[156:159], v[216:219], v[36:39]
	ds_read_b128 v[186:189], v250 offset:36864
	v_mfma_f32_16x16x32_bf16 v[28:31], v[156:159], v[220:223], v[28:31]
	ds_read_b128 v[192:195], v250 offset:38912
	v_mfma_f32_16x16x32_bf16 v[20:23], v[156:159], v[224:227], v[20:23]
	v_mfma_f32_16x16x32_bf16 v[12:15], v[156:159], v[228:231], v[12:15]
	v_mfma_f32_16x16x32_bf16 v[8:11], v[170:173], v[216:219], v[8:11]
	v_mfma_f32_16x16x32_bf16 v[4:7], v[170:173], v[220:223], v[4:7]
	v_mfma_f32_16x16x32_bf16 v[0:3], v[170:173], v[224:227], v[0:3]
	v_mfma_f32_16x16x32_bf16 v[108:111], v[170:173], v[228:231], v[108:111]
	s_waitcnt lgkmcnt(0)
	v_mfma_f32_16x16x32_bf16 v[124:127], v[198:201], v[178:181], v[124:127]
	ds_read_b128 v[216:219], v250 offset:40960
	v_mfma_f32_16x16x32_bf16 v[120:123], v[198:201], v[182:185], v[120:123]
	ds_read_b128 v[220:223], v250 offset:43008
	v_mfma_f32_16x16x32_bf16 v[116:119], v[198:201], v[186:189], v[116:119]
	ds_read_b128 v[224:227], v250 offset:45056
	v_mfma_f32_16x16x32_bf16 v[112:115], v[198:201], v[192:195], v[112:115]
	ds_read_b128 v[228:231], v250 offset:47104
	v_mfma_f32_16x16x32_bf16 v[104:107], v[204:207], v[178:181], v[104:107]
	v_mfma_f32_16x16x32_bf16 v[96:99], v[204:207], v[182:185], v[96:99]
	v_mfma_f32_16x16x32_bf16 v[88:91], v[204:207], v[186:189], v[88:91]
	v_mfma_f32_16x16x32_bf16 v[80:83], v[204:207], v[192:195], v[80:83]
	v_mfma_f32_16x16x32_bf16 v[72:75], v[208:211], v[178:181], v[72:75]
	v_mfma_f32_16x16x32_bf16 v[64:67], v[208:211], v[182:185], v[64:67]
	v_mfma_f32_16x16x32_bf16 v[56:59], v[208:211], v[186:189], v[56:59]
	v_mfma_f32_16x16x32_bf16 v[48:51], v[208:211], v[192:195], v[48:51]
	v_mfma_f32_16x16x32_bf16 v[40:43], v[212:215], v[178:181], v[40:43]
	v_mfma_f32_16x16x32_bf16 v[32:35], v[212:215], v[182:185], v[32:35]
	v_mfma_f32_16x16x32_bf16 v[24:27], v[212:215], v[186:189], v[24:27]
	v_mfma_f32_16x16x32_bf16 v[16:19], v[212:215], v[192:195], v[16:19]
	s_waitcnt lgkmcnt(0)
	v_mfma_f32_16x16x32_bf16 v[100:103], v[198:201], v[216:219], v[100:103]
	v_mfma_f32_16x16x32_bf16 v[92:95], v[198:201], v[220:223], v[92:95]
	v_mfma_f32_16x16x32_bf16 v[84:87], v[198:201], v[224:227], v[84:87]
	v_mfma_f32_16x16x32_bf16 v[76:79], v[198:201], v[228:231], v[76:79]
	v_mfma_f32_16x16x32_bf16 v[68:71], v[204:207], v[216:219], v[68:71]
	v_mfma_f32_16x16x32_bf16 v[60:63], v[204:207], v[220:223], v[60:63]
	v_mfma_f32_16x16x32_bf16 v[52:55], v[204:207], v[224:227], v[52:55]
	v_mfma_f32_16x16x32_bf16 v[44:47], v[204:207], v[228:231], v[44:47]
	v_mfma_f32_16x16x32_bf16 v[36:39], v[208:211], v[216:219], v[36:39]
	v_mfma_f32_16x16x32_bf16 v[28:31], v[208:211], v[220:223], v[28:31]
	v_mfma_f32_16x16x32_bf16 v[20:23], v[208:211], v[224:227], v[20:23]
	v_mfma_f32_16x16x32_bf16 v[12:15], v[208:211], v[228:231], v[12:15]
	s_add_u32 s2, s2, 0x80
	s_addc_u32 s3, s3, 0
	s_cmpk_eq_i32 s2, 0x780
	s_mov_b32 s4, s5
	v_mfma_f32_16x16x32_bf16 v[8:11], v[212:215], v[216:219], v[8:11]
	v_mfma_f32_16x16x32_bf16 v[4:7], v[212:215], v[220:223], v[4:7]
	v_mfma_f32_16x16x32_bf16 v[0:3], v[212:215], v[224:227], v[0:3]
	v_mfma_f32_16x16x32_bf16 v[108:111], v[212:215], v[228:231], v[108:111]
	s_cbranch_scc0 .LBB0_1074
	s_add_i32 s2, 0, 0x10000
	v_add_u32_e32 v136, s2, v145
	v_add_u32_e32 v174, s2, v144
	v_add_u32_e32 v137, v136, v143
	v_add_u32_e32 v143, v174, v143
	s_waitcnt vmcnt(0)
	s_barrier
	ds_read_b128 v[128:131], v137 offset:38912
	ds_read_b128 v[132:135], v137 offset:36864
	ds_read_b128 v[146:149], v137 offset:34816
	ds_read_b128 v[150:153], v137 offset:32768
	ds_read_b128 v[154:157], v143 offset:6144
	ds_read_b128 v[158:161], v143 offset:4096
	ds_read_b128 v[170:173], v143 offset:2048
	ds_read_b128 v[178:181], v143
	s_waitcnt lgkmcnt(0)
	v_mfma_f32_16x16x32_bf16 v[124:127], v[178:181], v[150:153], v[124:127]
	v_mfma_f32_16x16x32_bf16 v[120:123], v[178:181], v[146:149], v[120:123]
	v_mfma_f32_16x16x32_bf16 v[116:119], v[178:181], v[132:135], v[116:119]
	v_mfma_f32_16x16x32_bf16 v[112:115], v[178:181], v[128:131], v[112:115]
	v_mfma_f32_16x16x32_bf16 v[104:107], v[170:173], v[150:153], v[104:107]
	v_mfma_f32_16x16x32_bf16 v[72:75], v[158:161], v[150:153], v[72:75]
	v_mfma_f32_16x16x32_bf16 v[64:67], v[158:161], v[146:149], v[64:67]
	v_mfma_f32_16x16x32_bf16 v[56:59], v[158:161], v[132:135], v[56:59]
	v_mfma_f32_16x16x32_bf16 v[48:51], v[158:161], v[128:131], v[48:51]
	v_mfma_f32_16x16x32_bf16 v[182:185], v[170:173], v[146:149], v[96:99]
	v_mfma_f32_16x16x32_bf16 v[186:189], v[170:173], v[132:135], v[88:91]
	v_mfma_f32_16x16x32_bf16 v[192:195], v[170:173], v[128:131], v[80:83]
	v_mfma_f32_16x16x32_bf16 v[150:153], v[154:157], v[150:153], v[40:43]
	v_mfma_f32_16x16x32_bf16 v[144:147], v[154:157], v[146:149], v[32:35]
	v_mfma_f32_16x16x32_bf16 v[132:135], v[154:157], v[132:135], v[24:27]
	v_mfma_f32_16x16x32_bf16 v[128:131], v[154:157], v[128:131], v[16:19]
	s_nop 2
	ds_read_b128 v[16:19], v137 offset:40960
	ds_read_b128 v[24:27], v137 offset:43008
	ds_read_b128 v[32:35], v137 offset:45056
	ds_read_b128 v[40:43], v137 offset:47104
	s_waitcnt lgkmcnt(0)
	v_mfma_f32_16x16x32_bf16 v[100:103], v[178:181], v[16:19], v[100:103]
	v_mfma_f32_16x16x32_bf16 v[92:95], v[178:181], v[24:27], v[92:95]
	v_mfma_f32_16x16x32_bf16 v[198:201], v[178:181], v[32:35], v[84:87]
	v_mfma_f32_16x16x32_bf16 v[76:79], v[178:181], v[40:43], v[76:79]
	v_mfma_f32_16x16x32_bf16 v[68:71], v[170:173], v[16:19], v[68:71]
	v_mfma_f32_16x16x32_bf16 v[60:63], v[170:173], v[24:27], v[60:63]
	v_mfma_f32_16x16x32_bf16 v[178:181], v[170:173], v[32:35], v[52:55]
	v_mfma_f32_16x16x32_bf16 v[44:47], v[170:173], v[40:43], v[44:47]
	v_mfma_f32_16x16x32_bf16 v[170:173], v[158:161], v[16:19], v[36:39]
	v_mfma_f32_16x16x32_bf16 v[204:207], v[158:161], v[24:27], v[28:31]
	v_mfma_f32_16x16x32_bf16 v[208:211], v[158:161], v[32:35], v[20:23]
	v_mfma_f32_16x16x32_bf16 v[158:161], v[158:161], v[40:43], v[12:15]
	v_mfma_f32_16x16x32_bf16 v[212:215], v[154:157], v[16:19], v[8:11]
	v_mfma_f32_16x16x32_bf16 v[216:219], v[154:157], v[24:27], v[4:7]
	v_mfma_f32_16x16x32_bf16 v[220:223], v[154:157], v[32:35], v[0:3]
	v_mfma_f32_16x16x32_bf16 v[154:157], v[154:157], v[40:43], v[108:111]
	s_nop 1
	v_add_u32_e32 v0, v174, v142
	v_add_u32_e32 v136, v136, v142
	ds_read_b128 v[108:111], v0
	ds_read_b128 v[224:227], v0 offset:2048
	ds_read_b128 v[228:231], v0 offset:4096
	ds_read_b128 v[232:235], v0 offset:6144
	ds_read_b128 v[0:3], v136 offset:32768
	ds_read_b128 v[4:7], v136 offset:34816
	ds_read_b128 v[236:239], v136 offset:36864
	ds_read_b128 v[240:243], v136 offset:38912
	s_waitcnt lgkmcnt(0)
	v_mfma_f32_16x16x32_bf16 v[88:91], v[108:111], v[0:3], v[124:127]
	v_mfma_f32_16x16x32_bf16 v[96:99], v[108:111], v[4:7], v[120:123]
	v_mfma_f32_16x16x32_bf16 v[80:83], v[108:111], v[236:239], v[116:119]
	v_mfma_f32_16x16x32_bf16 v[84:87], v[108:111], v[240:243], v[112:115]
	v_mfma_f32_16x16x32_bf16 v[40:43], v[224:227], v[0:3], v[104:107]
	v_mfma_f32_16x16x32_bf16 v[52:55], v[224:227], v[4:7], v[182:185]
	v_mfma_f32_16x16x32_bf16 v[32:35], v[224:227], v[236:239], v[186:189]
	v_mfma_f32_16x16x32_bf16 v[36:39], v[224:227], v[240:243], v[192:195]
	v_mfma_f32_16x16x32_bf16 v[24:27], v[228:231], v[0:3], v[72:75]
	v_mfma_f32_16x16x32_bf16 v[28:31], v[228:231], v[4:7], v[64:67]
	v_mfma_f32_16x16x32_bf16 v[16:19], v[228:231], v[236:239], v[56:59]
	v_mfma_f32_16x16x32_bf16 v[20:23], v[228:231], v[240:243], v[48:51]
	v_mfma_f32_16x16x32_bf16 v[8:11], v[232:235], v[0:3], v[150:153]
	v_mfma_f32_16x16x32_bf16 v[12:15], v[232:235], v[4:7], v[144:147]
	v_mfma_f32_16x16x32_bf16 v[0:3], v[232:235], v[236:239], v[132:135]
	v_mfma_f32_16x16x32_bf16 v[4:7], v[232:235], v[240:243], v[128:131]
	ds_read_b128 v[48:51], v136 offset:40960
	ds_read_b128 v[64:67], v136 offset:43008
	s_nop 0
	ds_read_b128 v[128:131], v136 offset:45056
	ds_read_b128 v[132:135], v136 offset:47104
	s_waitcnt lgkmcnt(0)
	v_mfma_f32_16x16x32_bf16 v[104:107], v[224:227], v[48:51], v[68:71]
	v_cmp_ne_u32_e32 vcc, 0, v138
	v_cmp_eq_u32_e64 s[2:3], 0, v138
	s_waitcnt vmcnt(0)
	v_lshl_or_b32 v68, v140, 2, v141
	v_lshl_add_u32 v69, v139, 2, 0
	v_mfma_f32_16x16x32_bf16 v[120:123], v[108:111], v[48:51], v[100:103]
	s_barrier
	v_mfma_f32_16x16x32_bf16 v[124:127], v[108:111], v[64:67], v[92:95]
	v_mfma_f32_16x16x32_bf16 v[112:115], v[108:111], v[128:131], v[198:201]
	v_mfma_f32_16x16x32_bf16 v[116:119], v[108:111], v[132:135], v[76:79]
	v_mfma_f32_16x16x32_bf16 v[108:111], v[224:227], v[64:67], v[60:63]
	v_mfma_f32_16x16x32_bf16 v[92:95], v[224:227], v[128:131], v[178:181]
	v_mfma_f32_16x16x32_bf16 v[100:103], v[224:227], v[132:135], v[44:47]
	s_nop 1
	v_lshl_add_u32 v178, v68, 9, v69
	v_add_u32_e32 v179, 0x400, v178
	v_add_u32_e32 v176, 0x2000, v178
	v_mfma_f32_16x16x32_bf16 v[56:59], v[228:231], v[48:51], v[170:173]
	v_add_u32_e32 v175, 0x2400, v178
	v_add_u32_e32 v174, 0x4000, v178
	v_mfma_f32_16x16x32_bf16 v[60:63], v[228:231], v[64:67], v[204:207]
	v_add_u32_e32 v173, 0x4400, v178
	v_add_u32_e32 v172, 0x6000, v178
	v_add_u32_e32 v171, 0x6400, v178
	v_mfma_f32_16x16x32_bf16 v[44:47], v[228:231], v[128:131], v[208:211]
	v_mfma_f32_16x16x32_bf16 v[72:75], v[228:231], v[132:135], v[158:161]
	v_mfma_f32_16x16x32_bf16 v[48:51], v[232:235], v[48:51], v[212:215]
	v_mfma_f32_16x16x32_bf16 v[64:67], v[232:235], v[64:67], v[216:219]
	v_mfma_f32_16x16x32_bf16 v[68:71], v[232:235], v[128:131], v[220:223]
	v_mfma_f32_16x16x32_bf16 v[76:79], v[232:235], v[132:135], v[154:157]
	s_and_saveexec_b64 s[4:5], s[2:3]
	s_cbranch_execz .LBB0_1077
	ds_write2_b32 v178, v88, v96 offset1:16
	ds_write2_b32 v178, v89, v97 offset0:128 offset1:144
	ds_write2_b32 v179, v90, v98 offset1:16
	ds_write2_b32 v179, v91, v99 offset0:128 offset1:144
	ds_write2_b32 v178, v80, v84 offset0:32 offset1:48
	ds_write2_b32 v178, v81, v85 offset0:160 offset1:176
	ds_write2_b32 v179, v82, v86 offset0:32 offset1:48
	ds_write2_b32 v179, v83, v87 offset0:160 offset1:176
	ds_write2_b32 v178, v120, v124 offset0:64 offset1:80
	ds_write2_b32 v178, v121, v125 offset0:192 offset1:208
	ds_write2_b32 v179, v122, v126 offset0:64 offset1:80
	ds_write2_b32 v179, v123, v127 offset0:192 offset1:208
	ds_write2_b32 v178, v112, v116 offset0:96 offset1:112
	ds_write2_b32 v178, v113, v117 offset0:224 offset1:240
	ds_write2_b32 v179, v114, v118 offset0:96 offset1:112
	ds_write2_b32 v179, v115, v119 offset0:224 offset1:240
	ds_write2_b32 v176, v40, v52 offset1:16
	ds_write2_b32 v176, v41, v53 offset0:128 offset1:144
	ds_write2_b32 v175, v42, v54 offset1:16
	ds_write2_b32 v175, v43, v55 offset0:128 offset1:144
	ds_write2_b32 v176, v32, v36 offset0:32 offset1:48
	ds_write2_b32 v176, v33, v37 offset0:160 offset1:176
	ds_write2_b32 v175, v34, v38 offset0:32 offset1:48
	ds_write2_b32 v175, v35, v39 offset0:160 offset1:176
	ds_write2_b32 v176, v104, v108 offset0:64 offset1:80
	ds_write2_b32 v176, v105, v109 offset0:192 offset1:208
	ds_write2_b32 v175, v106, v110 offset0:64 offset1:80
	ds_write2_b32 v175, v107, v111 offset0:192 offset1:208
	ds_write2_b32 v176, v92, v100 offset0:96 offset1:112
	ds_write2_b32 v176, v93, v101 offset0:224 offset1:240
	ds_write2_b32 v175, v94, v102 offset0:96 offset1:112
	ds_write2_b32 v175, v95, v103 offset0:224 offset1:240
	ds_write2_b32 v174, v24, v28 offset1:16
	ds_write2_b32 v174, v25, v29 offset0:128 offset1:144
	ds_write2_b32 v173, v26, v30 offset1:16
	ds_write2_b32 v173, v27, v31 offset0:128 offset1:144
	ds_write2_b32 v174, v16, v20 offset0:32 offset1:48
	ds_write2_b32 v174, v17, v21 offset0:160 offset1:176
	ds_write2_b32 v173, v18, v22 offset0:32 offset1:48
	ds_write2_b32 v173, v19, v23 offset0:160 offset1:176
	ds_write2_b32 v174, v56, v60 offset0:64 offset1:80
	ds_write2_b32 v174, v57, v61 offset0:192 offset1:208
	ds_write2_b32 v173, v58, v62 offset0:64 offset1:80
	ds_write2_b32 v173, v59, v63 offset0:192 offset1:208
	ds_write2_b32 v174, v44, v72 offset0:96 offset1:112
	ds_write2_b32 v174, v45, v73 offset0:224 offset1:240
	ds_write2_b32 v173, v46, v74 offset0:96 offset1:112
	ds_write2_b32 v173, v47, v75 offset0:224 offset1:240
	ds_write2_b32 v172, v8, v12 offset1:16
	ds_write2_b32 v172, v9, v13 offset0:128 offset1:144
	ds_write2_b32 v171, v10, v14 offset1:16
	ds_write2_b32 v171, v11, v15 offset0:128 offset1:144
	ds_write2_b32 v172, v0, v4 offset0:32 offset1:48
	ds_write2_b32 v172, v1, v5 offset0:160 offset1:176
	ds_write2_b32 v171, v2, v6 offset0:32 offset1:48
	ds_write2_b32 v171, v3, v7 offset0:160 offset1:176
	ds_write2_b32 v172, v48, v64 offset0:64 offset1:80
	ds_write2_b32 v172, v49, v65 offset0:192 offset1:208
	ds_write2_b32 v171, v50, v66 offset0:64 offset1:80
	ds_write2_b32 v171, v51, v67 offset0:192 offset1:208
	ds_write2_b32 v172, v68, v76 offset0:96 offset1:112
	ds_write2_b32 v172, v69, v77 offset0:224 offset1:240
	ds_write2_b32 v171, v70, v78 offset0:96 offset1:112
	ds_write2_b32 v171, v71, v79 offset0:224 offset1:240

.LBB0_1143:
	s_add_i32 s11, s10, 0x10000
	s_and_b32 s19, s11, 0x10000
	s_waitcnt vmcnt(0)
	s_barrier
	s_and_b32 s10, s10, 0x10000
	s_add_i32 s10, s10, 0
	v_add_u32_e32 v151, s10, v149
	v_add_u32_e32 v164, v151, v147
	ds_read_b128 v[152:155], v164
	ds_read_b128 v[156:159], v164 offset:2048
	ds_read_b128 v[160:163], v164 offset:4096
	ds_read_b128 v[164:167], v164 offset:6144
	v_add_u32_e32 v251, v151, v146
	v_add_u32_e32 v176, s10, v148
	v_add_u32_e32 v186, v176, v147
	ds_read_b128 v[168:171], v186 offset:32768
	ds_read_b128 v[172:175], v186 offset:34816
	ds_read_b128 v[178:181], v186 offset:36864
	ds_read_b128 v[182:185], v186 offset:38912
	v_add_u32_e32 v250, v176, v146
	v_add_u32_e32 v254, s19, v150
	v_add_u32_e32 v228, 0x2000, v254
	v_readfirstlane_b32 s19, v254
	v_lshl_add_u64 v[188:189], v[128:129], 0, s[2:3]
	s_mov_b32 m0, s19
	v_readfirstlane_b32 s19, v228
	v_add_u32_e32 v228, 0x4000, v254
	global_load_lds_dwordx4 v[188:189], off
	v_lshl_add_u64 v[188:189], v[130:131], 0, s[2:3]
	s_mov_b32 m0, s19
	s_waitcnt lgkmcnt(0)
	v_mfma_f32_16x16x32_bf16 v[124:127], v[152:155], v[168:171], v[124:127]
	ds_read_b128 v[212:215], v186 offset:40960
	v_mfma_f32_16x16x32_bf16 v[120:123], v[152:155], v[172:175], v[120:123]
	ds_read_b128 v[216:219], v186 offset:43008
	v_readfirstlane_b32 s19, v228
	v_add_u32_e32 v228, 0x6000, v254
	v_mfma_f32_16x16x32_bf16 v[116:119], v[152:155], v[178:181], v[116:119]
	ds_read_b128 v[220:223], v186 offset:45056
	global_load_lds_dwordx4 v[188:189], off
	v_lshl_add_u64 v[188:189], v[132:133], 0, s[2:3]
	v_mfma_f32_16x16x32_bf16 v[112:115], v[152:155], v[182:185], v[112:115]
	ds_read_b128 v[224:227], v186 offset:47104
	s_mov_b32 m0, s19
	v_readfirstlane_b32 s19, v228
	v_mfma_f32_16x16x32_bf16 v[104:107], v[156:159], v[168:171], v[104:107]
	global_load_lds_dwordx4 v[188:189], off
	v_lshl_add_u64 v[188:189], v[134:135], 0, s[2:3]
	v_mfma_f32_16x16x32_bf16 v[96:99], v[156:159], v[172:175], v[96:99]
	s_mov_b32 m0, s19
	v_add_u32_e32 v253, 0x8000, v254
	v_mfma_f32_16x16x32_bf16 v[88:91], v[156:159], v[178:181], v[88:91]
	global_load_lds_dwordx4 v[188:189], off
	v_lshl_add_u64 v[188:189], v[136:137], 0, s[2:3]
	v_mfma_f32_16x16x32_bf16 v[80:83], v[156:159], v[182:185], v[80:83]
	s_mov_b64 s[20:21], 0x1320080
	v_readfirstlane_b32 s19, v253
	v_mfma_f32_16x16x32_bf16 v[72:75], v[160:163], v[168:171], v[72:75]
	v_add_u32_e32 v253, 0xa000, v254
	v_lshl_add_u64 v[228:229], v[188:189], 0, s[20:21]
	v_mfma_f32_16x16x32_bf16 v[64:67], v[160:163], v[172:175], v[64:67]
	s_mov_b32 m0, s19
	s_mov_b64 s[20:21], 0x1378080
	v_mfma_f32_16x16x32_bf16 v[56:59], v[160:163], v[178:181], v[56:59]
	v_readfirstlane_b32 s19, v253
	v_add_u32_e32 v253, 0xc000, v254
	v_mfma_f32_16x16x32_bf16 v[48:51], v[160:163], v[182:185], v[48:51]
	global_load_lds_dwordx4 v[228:229], off
	v_lshl_add_u64 v[228:229], v[188:189], 0, s[20:21]
	v_mfma_f32_16x16x32_bf16 v[40:43], v[164:167], v[168:171], v[40:43]
	s_mov_b32 m0, s19
	s_mov_b64 s[20:21], 0x13d0080
	v_mfma_f32_16x16x32_bf16 v[32:35], v[164:167], v[172:175], v[32:35]
	v_readfirstlane_b32 s19, v253
	v_add_u32_e32 v254, 0xe000, v254
	v_mfma_f32_16x16x32_bf16 v[24:27], v[164:167], v[178:181], v[24:27]
	global_load_lds_dwordx4 v[228:229], off
	v_lshl_add_u64 v[228:229], v[188:189], 0, s[20:21]
	v_mfma_f32_16x16x32_bf16 v[16:19], v[164:167], v[182:185], v[16:19]
	s_mov_b32 m0, s19
	s_mov_b64 s[20:21], 0x1428080
	s_waitcnt lgkmcnt(0)
	v_mfma_f32_16x16x32_bf16 v[100:103], v[152:155], v[212:215], v[100:103]
	ds_read_b128 v[192:195], v251
	v_readfirstlane_b32 s19, v254
	global_load_lds_dwordx4 v[228:229], off
	v_mfma_f32_16x16x32_bf16 v[92:95], v[152:155], v[216:219], v[92:95]
	ds_read_b128 v[198:201], v251 offset:2048
	v_lshl_add_u64 v[188:189], v[188:189], 0, s[20:21]
	s_mov_b32 m0, s19
	v_mfma_f32_16x16x32_bf16 v[84:87], v[152:155], v[220:223], v[84:87]
	ds_read_b128 v[204:207], v251 offset:4096
	global_load_lds_dwordx4 v[188:189], off
	v_mfma_f32_16x16x32_bf16 v[76:79], v[152:155], v[224:227], v[76:79]
	ds_read_b128 v[208:211], v251 offset:6144
	v_mfma_f32_16x16x32_bf16 v[68:71], v[156:159], v[212:215], v[68:71]
	v_mfma_f32_16x16x32_bf16 v[60:63], v[156:159], v[216:219], v[60:63]
	v_mfma_f32_16x16x32_bf16 v[52:55], v[156:159], v[220:223], v[52:55]
	ds_read_b128 v[168:171], v250 offset:32768
	v_mfma_f32_16x16x32_bf16 v[44:47], v[156:159], v[224:227], v[44:47]
	ds_read_b128 v[172:175], v250 offset:34816
	v_mfma_f32_16x16x32_bf16 v[36:39], v[160:163], v[212:215], v[36:39]
	ds_read_b128 v[178:181], v250 offset:36864
	v_mfma_f32_16x16x32_bf16 v[28:31], v[160:163], v[216:219], v[28:31]
	ds_read_b128 v[182:185], v250 offset:38912
	v_mfma_f32_16x16x32_bf16 v[20:23], v[160:163], v[220:223], v[20:23]
	v_mfma_f32_16x16x32_bf16 v[12:15], v[160:163], v[224:227], v[12:15]
	v_mfma_f32_16x16x32_bf16 v[8:11], v[164:167], v[212:215], v[8:11]
	v_mfma_f32_16x16x32_bf16 v[4:7], v[164:167], v[216:219], v[4:7]
	v_mfma_f32_16x16x32_bf16 v[0:3], v[164:167], v[220:223], v[0:3]
	v_mfma_f32_16x16x32_bf16 v[108:111], v[164:167], v[224:227], v[108:111]
	s_waitcnt lgkmcnt(0)
	v_mfma_f32_16x16x32_bf16 v[124:127], v[192:195], v[168:171], v[124:127]
	ds_read_b128 v[212:215], v250 offset:40960
	v_mfma_f32_16x16x32_bf16 v[120:123], v[192:195], v[172:175], v[120:123]
	ds_read_b128 v[216:219], v250 offset:43008
	v_mfma_f32_16x16x32_bf16 v[116:119], v[192:195], v[178:181], v[116:119]
	ds_read_b128 v[220:223], v250 offset:45056
	v_mfma_f32_16x16x32_bf16 v[112:115], v[192:195], v[182:185], v[112:115]
	ds_read_b128 v[224:227], v250 offset:47104
	v_mfma_f32_16x16x32_bf16 v[104:107], v[198:201], v[168:171], v[104:107]
	v_mfma_f32_16x16x32_bf16 v[96:99], v[198:201], v[172:175], v[96:99]
	v_mfma_f32_16x16x32_bf16 v[88:91], v[198:201], v[178:181], v[88:91]
	v_mfma_f32_16x16x32_bf16 v[80:83], v[198:201], v[182:185], v[80:83]
	v_mfma_f32_16x16x32_bf16 v[72:75], v[204:207], v[168:171], v[72:75]
	v_mfma_f32_16x16x32_bf16 v[64:67], v[204:207], v[172:175], v[64:67]
	v_mfma_f32_16x16x32_bf16 v[56:59], v[204:207], v[178:181], v[56:59]
	v_mfma_f32_16x16x32_bf16 v[48:51], v[204:207], v[182:185], v[48:51]
	v_mfma_f32_16x16x32_bf16 v[40:43], v[208:211], v[168:171], v[40:43]
	v_mfma_f32_16x16x32_bf16 v[32:35], v[208:211], v[172:175], v[32:35]
	v_mfma_f32_16x16x32_bf16 v[24:27], v[208:211], v[178:181], v[24:27]
	v_mfma_f32_16x16x32_bf16 v[16:19], v[208:211], v[182:185], v[16:19]
	s_waitcnt lgkmcnt(0)
	v_mfma_f32_16x16x32_bf16 v[100:103], v[192:195], v[212:215], v[100:103]
	v_mfma_f32_16x16x32_bf16 v[92:95], v[192:195], v[216:219], v[92:95]
	v_mfma_f32_16x16x32_bf16 v[84:87], v[192:195], v[220:223], v[84:87]
	v_mfma_f32_16x16x32_bf16 v[76:79], v[192:195], v[224:227], v[76:79]
	v_mfma_f32_16x16x32_bf16 v[68:71], v[198:201], v[212:215], v[68:71]
	v_mfma_f32_16x16x32_bf16 v[60:63], v[198:201], v[216:219], v[60:63]
	v_mfma_f32_16x16x32_bf16 v[52:55], v[198:201], v[220:223], v[52:55]
	v_mfma_f32_16x16x32_bf16 v[44:47], v[198:201], v[224:227], v[44:47]
	v_mfma_f32_16x16x32_bf16 v[36:39], v[204:207], v[212:215], v[36:39]
	v_mfma_f32_16x16x32_bf16 v[28:31], v[204:207], v[216:219], v[28:31]
	v_mfma_f32_16x16x32_bf16 v[20:23], v[204:207], v[220:223], v[20:23]
	v_mfma_f32_16x16x32_bf16 v[12:15], v[204:207], v[224:227], v[12:15]
	s_add_u32 s2, s2, 0x80
	s_addc_u32 s3, s3, 0
	s_cmpk_eq_i32 s2, 0x1580
	s_mov_b32 s10, s11
	v_mfma_f32_16x16x32_bf16 v[8:11], v[208:211], v[212:215], v[8:11]
	v_mfma_f32_16x16x32_bf16 v[4:7], v[208:211], v[216:219], v[4:7]
	v_mfma_f32_16x16x32_bf16 v[0:3], v[208:211], v[220:223], v[0:3]
	v_mfma_f32_16x16x32_bf16 v[108:111], v[208:211], v[224:227], v[108:111]
	s_cbranch_scc0 .LBB0_1143
	s_add_i32 s2, 0, 0x10000
	v_add_u32_e32 v136, s2, v149
	v_add_u32_e32 v137, v136, v147
	s_waitcnt vmcnt(0)
	s_barrier
	ds_read_b128 v[128:131], v137
	ds_read_b128 v[132:135], v137 offset:2048
	ds_read_b128 v[150:153], v137 offset:4096
	ds_read_b128 v[154:157], v137 offset:6144
	v_add_u32_e32 v137, s2, v148
	v_add_u32_e32 v147, v137, v147
	ds_read_b128 v[158:161], v147 offset:32768
	ds_read_b128 v[162:165], v147 offset:34816
	ds_read_b128 v[166:169], v147 offset:36864
	ds_read_b128 v[170:173], v147 offset:38912
	s_waitcnt lgkmcnt(0)
	v_mfma_f32_16x16x32_bf16 v[124:127], v[128:131], v[158:161], v[124:127]
	v_mfma_f32_16x16x32_bf16 v[120:123], v[128:131], v[162:165], v[120:123]
	v_mfma_f32_16x16x32_bf16 v[116:119], v[128:131], v[166:169], v[116:119]
	v_mfma_f32_16x16x32_bf16 v[112:115], v[128:131], v[170:173], v[112:115]
	v_mfma_f32_16x16x32_bf16 v[104:107], v[132:135], v[158:161], v[104:107]
	v_mfma_f32_16x16x32_bf16 v[72:75], v[150:153], v[158:161], v[72:75]
	v_mfma_f32_16x16x32_bf16 v[64:67], v[150:153], v[162:165], v[64:67]
	v_mfma_f32_16x16x32_bf16 v[56:59], v[150:153], v[166:169], v[56:59]
	v_mfma_f32_16x16x32_bf16 v[48:51], v[150:153], v[170:173], v[48:51]
	v_mfma_f32_16x16x32_bf16 v[178:181], v[132:135], v[162:165], v[96:99]
	v_mfma_f32_16x16x32_bf16 v[182:185], v[132:135], v[166:169], v[88:91]
	v_mfma_f32_16x16x32_bf16 v[186:189], v[132:135], v[170:173], v[80:83]
	v_mfma_f32_16x16x32_bf16 v[158:161], v[154:157], v[158:161], v[40:43]
	v_mfma_f32_16x16x32_bf16 v[162:165], v[154:157], v[162:165], v[32:35]
	v_mfma_f32_16x16x32_bf16 v[166:169], v[154:157], v[166:169], v[24:27]
	v_mfma_f32_16x16x32_bf16 v[170:173], v[154:157], v[170:173], v[16:19]
	s_nop 2
	ds_read_b128 v[16:19], v147 offset:40960
	ds_read_b128 v[24:27], v147 offset:43008
	ds_read_b128 v[32:35], v147 offset:45056
	ds_read_b128 v[40:43], v147 offset:47104
	s_waitcnt lgkmcnt(0)
	v_mfma_f32_16x16x32_bf16 v[100:103], v[128:131], v[16:19], v[100:103]
	v_mfma_f32_16x16x32_bf16 v[92:95], v[128:131], v[24:27], v[92:95]
	v_mfma_f32_16x16x32_bf16 v[192:195], v[128:131], v[32:35], v[84:87]
	v_mfma_f32_16x16x32_bf16 v[76:79], v[128:131], v[40:43], v[76:79]
	v_mfma_f32_16x16x32_bf16 v[68:71], v[132:135], v[16:19], v[68:71]
	v_mfma_f32_16x16x32_bf16 v[60:63], v[132:135], v[24:27], v[60:63]
	v_mfma_f32_16x16x32_bf16 v[128:131], v[132:135], v[32:35], v[52:55]
	v_mfma_f32_16x16x32_bf16 v[44:47], v[132:135], v[40:43], v[44:47]
	v_mfma_f32_16x16x32_bf16 v[132:135], v[150:153], v[16:19], v[36:39]
	v_mfma_f32_16x16x32_bf16 v[198:201], v[150:153], v[24:27], v[28:31]
	v_mfma_f32_16x16x32_bf16 v[204:207], v[150:153], v[32:35], v[20:23]
	v_mfma_f32_16x16x32_bf16 v[148:151], v[150:153], v[40:43], v[12:15]
	v_mfma_f32_16x16x32_bf16 v[208:211], v[154:157], v[16:19], v[8:11]
	v_mfma_f32_16x16x32_bf16 v[212:215], v[154:157], v[24:27], v[4:7]
	v_mfma_f32_16x16x32_bf16 v[216:219], v[154:157], v[32:35], v[0:3]
	v_mfma_f32_16x16x32_bf16 v[154:157], v[154:157], v[40:43], v[108:111]
	s_nop 1
	v_add_u32_e32 v0, v136, v146
	v_add_u32_e32 v136, v137, v146
	ds_read_b128 v[108:111], v0
	ds_read_b128 v[220:223], v0 offset:2048
	ds_read_b128 v[224:227], v0 offset:4096
	ds_read_b128 v[228:231], v0 offset:6144
	ds_read_b128 v[0:3], v136 offset:32768
	ds_read_b128 v[4:7], v136 offset:34816
	ds_read_b128 v[232:235], v136 offset:36864
	ds_read_b128 v[236:239], v136 offset:38912
	s_waitcnt lgkmcnt(0)
	v_mfma_f32_16x16x32_bf16 v[88:91], v[108:111], v[0:3], v[124:127]
	v_mfma_f32_16x16x32_bf16 v[96:99], v[108:111], v[4:7], v[120:123]
	v_mfma_f32_16x16x32_bf16 v[80:83], v[108:111], v[232:235], v[116:119]
	v_mfma_f32_16x16x32_bf16 v[84:87], v[108:111], v[236:239], v[112:115]
	v_mfma_f32_16x16x32_bf16 v[40:43], v[220:223], v[0:3], v[104:107]
	v_mfma_f32_16x16x32_bf16 v[52:55], v[220:223], v[4:7], v[178:181]
	v_mfma_f32_16x16x32_bf16 v[32:35], v[220:223], v[232:235], v[182:185]
	v_mfma_f32_16x16x32_bf16 v[36:39], v[220:223], v[236:239], v[186:189]
	v_mfma_f32_16x16x32_bf16 v[24:27], v[224:227], v[0:3], v[72:75]
	v_mfma_f32_16x16x32_bf16 v[28:31], v[224:227], v[4:7], v[64:67]
	v_mfma_f32_16x16x32_bf16 v[16:19], v[224:227], v[232:235], v[56:59]
	v_mfma_f32_16x16x32_bf16 v[20:23], v[224:227], v[236:239], v[48:51]
	v_mfma_f32_16x16x32_bf16 v[8:11], v[228:231], v[0:3], v[158:161]
	v_mfma_f32_16x16x32_bf16 v[12:15], v[228:231], v[4:7], v[162:165]
	v_mfma_f32_16x16x32_bf16 v[0:3], v[228:231], v[232:235], v[166:169]
	v_mfma_f32_16x16x32_bf16 v[4:7], v[228:231], v[236:239], v[170:173]
	ds_read_b128 v[48:51], v136 offset:40960
	ds_read_b128 v[64:67], v136 offset:43008
	ds_read_b128 v[158:161], v136 offset:45056
	ds_read_b128 v[162:165], v136 offset:47104
	s_waitcnt lgkmcnt(0)
	v_mfma_f32_16x16x32_bf16 v[104:107], v[220:223], v[48:51], v[68:71]
	v_cmp_ne_u32_e32 vcc, 0, v138
	v_cmp_eq_u32_e64 s[2:3], 0, v138
	s_waitcnt vmcnt(0)
	v_lshl_or_b32 v68, v140, 2, v141
	v_lshl_add_u32 v69, v139, 2, 0
	v_mfma_f32_16x16x32_bf16 v[120:123], v[108:111], v[48:51], v[100:103]
	v_lshl_add_u32 v152, v68, 9, v69
	v_add_u32_e32 v153, 0x400, v152
	v_add_u32_e32 v147, 0x6000, v152
	v_mfma_f32_16x16x32_bf16 v[124:127], v[108:111], v[64:67], v[92:95]
	v_add_u32_e32 v146, 0x6400, v152
	s_barrier
	v_mfma_f32_16x16x32_bf16 v[112:115], v[108:111], v[158:161], v[192:195]
	v_mfma_f32_16x16x32_bf16 v[116:119], v[108:111], v[162:165], v[76:79]
	v_mfma_f32_16x16x32_bf16 v[108:111], v[220:223], v[64:67], v[60:63]
	v_mfma_f32_16x16x32_bf16 v[92:95], v[220:223], v[158:161], v[128:131]
	v_mfma_f32_16x16x32_bf16 v[100:103], v[220:223], v[162:165], v[44:47]
	v_mfma_f32_16x16x32_bf16 v[56:59], v[224:227], v[48:51], v[132:135]
	v_mfma_f32_16x16x32_bf16 v[60:63], v[224:227], v[64:67], v[198:201]
	v_mfma_f32_16x16x32_bf16 v[44:47], v[224:227], v[158:161], v[204:207]
	v_mfma_f32_16x16x32_bf16 v[72:75], v[224:227], v[162:165], v[148:151]
	v_mfma_f32_16x16x32_bf16 v[48:51], v[228:231], v[48:51], v[208:211]
	s_nop 1
	v_add_u32_e32 v151, 0x2000, v152
	v_add_u32_e32 v150, 0x2400, v152
	v_add_u32_e32 v149, 0x4000, v152
	v_mfma_f32_16x16x32_bf16 v[64:67], v[228:231], v[64:67], v[212:215]
	v_add_u32_e32 v148, 0x4400, v152
	v_mfma_f32_16x16x32_bf16 v[68:71], v[228:231], v[158:161], v[216:219]
	v_mfma_f32_16x16x32_bf16 v[76:79], v[228:231], v[162:165], v[154:157]
	s_and_saveexec_b64 s[10:11], s[2:3]
	s_cbranch_execz .LBB0_1146
	ds_write2_b32 v152, v88, v96 offset1:16
	ds_write2_b32 v152, v89, v97 offset0:128 offset1:144
	ds_write2_b32 v153, v90, v98 offset1:16
	ds_write2_b32 v153, v91, v99 offset0:128 offset1:144
	ds_write2_b32 v152, v80, v84 offset0:32 offset1:48
	ds_write2_b32 v152, v81, v85 offset0:160 offset1:176
	ds_write2_b32 v153, v82, v86 offset0:32 offset1:48
	ds_write2_b32 v153, v83, v87 offset0:160 offset1:176
	ds_write2_b32 v152, v120, v124 offset0:64 offset1:80
	ds_write2_b32 v152, v121, v125 offset0:192 offset1:208
	ds_write2_b32 v153, v122, v126 offset0:64 offset1:80
	ds_write2_b32 v153, v123, v127 offset0:192 offset1:208
	ds_write2_b32 v152, v112, v116 offset0:96 offset1:112
	ds_write2_b32 v152, v113, v117 offset0:224 offset1:240
	ds_write2_b32 v153, v114, v118 offset0:96 offset1:112
	ds_write2_b32 v153, v115, v119 offset0:224 offset1:240
	ds_write2_b32 v151, v40, v52 offset1:16
	ds_write2_b32 v151, v41, v53 offset0:128 offset1:144
	ds_write2_b32 v150, v42, v54 offset1:16
	ds_write2_b32 v150, v43, v55 offset0:128 offset1:144
	ds_write2_b32 v151, v32, v36 offset0:32 offset1:48
	ds_write2_b32 v151, v33, v37 offset0:160 offset1:176
	ds_write2_b32 v150, v34, v38 offset0:32 offset1:48
	ds_write2_b32 v150, v35, v39 offset0:160 offset1:176
	ds_write2_b32 v151, v104, v108 offset0:64 offset1:80
	ds_write2_b32 v151, v105, v109 offset0:192 offset1:208
	ds_write2_b32 v150, v106, v110 offset0:64 offset1:80
	ds_write2_b32 v150, v107, v111 offset0:192 offset1:208
	ds_write2_b32 v151, v92, v100 offset0:96 offset1:112
	ds_write2_b32 v151, v93, v101 offset0:224 offset1:240
	ds_write2_b32 v150, v94, v102 offset0:96 offset1:112
	ds_write2_b32 v150, v95, v103 offset0:224 offset1:240
	ds_write2_b32 v149, v24, v28 offset1:16
	ds_write2_b32 v149, v25, v29 offset0:128 offset1:144
	ds_write2_b32 v148, v26, v30 offset1:16
	ds_write2_b32 v148, v27, v31 offset0:128 offset1:144
	ds_write2_b32 v149, v16, v20 offset0:32 offset1:48
	ds_write2_b32 v149, v17, v21 offset0:160 offset1:176
	ds_write2_b32 v148, v18, v22 offset0:32 offset1:48
	ds_write2_b32 v148, v19, v23 offset0:160 offset1:176
	ds_write2_b32 v149, v56, v60 offset0:64 offset1:80
	ds_write2_b32 v149, v57, v61 offset0:192 offset1:208
	ds_write2_b32 v148, v58, v62 offset0:64 offset1:80
	ds_write2_b32 v148, v59, v63 offset0:192 offset1:208
	ds_write2_b32 v149, v44, v72 offset0:96 offset1:112
	ds_write2_b32 v149, v45, v73 offset0:224 offset1:240
	ds_write2_b32 v148, v46, v74 offset0:96 offset1:112
	ds_write2_b32 v148, v47, v75 offset0:224 offset1:240
	ds_write2_b32 v147, v8, v12 offset1:16
	ds_write2_b32 v147, v9, v13 offset0:128 offset1:144
	ds_write2_b32 v146, v10, v14 offset1:16
	ds_write2_b32 v146, v11, v15 offset0:128 offset1:144
	ds_write2_b32 v147, v0, v4 offset0:32 offset1:48
	ds_write2_b32 v147, v1, v5 offset0:160 offset1:176
	ds_write2_b32 v146, v2, v6 offset0:32 offset1:48
	ds_write2_b32 v146, v3, v7 offset0:160 offset1:176
	ds_write2_b32 v147, v48, v64 offset0:64 offset1:80
	ds_write2_b32 v147, v49, v65 offset0:192 offset1:208
	ds_write2_b32 v146, v50, v66 offset0:64 offset1:80
	ds_write2_b32 v146, v51, v67 offset0:192 offset1:208
	ds_write2_b32 v147, v68, v76 offset0:96 offset1:112
	ds_write2_b32 v147, v69, v77 offset0:224 offset1:240
	ds_write2_b32 v146, v70, v78 offset0:96 offset1:112
	ds_write2_b32 v146, v71, v79 offset0:224 offset1:240
